# up: last reduction stage (xor 8) via bank-masked DPP row shifts on top of the ILP-ordered stack
# baseline (speedup 1.0000x reference)
; DI void up_math(const u32x4 (&W)[16], const u32 (&pj)[16], float* __restrict__ yrow, int lane) {
;   f2 y[8];
; #pragma unroll
;   for (int i = 0; i < 8; ++i) y[i] = f2{0.f, 0.f};
; #pragma unroll
;   for (int j = 0; j < 16; ++j) {
;     const float h = __uint_as_float(pj[j] << 16);
;     const f2 hh = {h, h};
; #pragma unroll
;     for (int d = 0; d < 4; ++d) {
;       f2 lo = __builtin_amdgcn_cvt_pk_f32_fp8((int)W[j][d], false);
;       f2 hi = __builtin_amdgcn_cvt_pk_f32_fp8((int)W[j][d], true);
;       y[2 * d] = lo * hh + y[2 * d];
;       y[2 * d + 1] = hi * hh + y[2 * d + 1];
;     }
;   }
.LBB0_826:
	s_add_i32 s44, s44, 2
	s_waitcnt vmcnt(16)
	v_cvt_pk_f32_fp8_e32 v[216:217], v128
	v_cvt_pk_f32_fp8_sdwa v[226:227], v128 src0_sel:WORD_1
	v_cvt_pk_f32_fp8_e32 v[228:229], v129
	v_cvt_pk_f32_fp8_sdwa v[128:129], v129 src0_sel:WORD_1
	v_cvt_pk_f32_fp8_e32 v[230:231], v130
	v_cvt_pk_f32_fp8_sdwa v[232:233], v130 src0_sel:WORD_1
	v_cvt_pk_f32_fp8_e32 v[234:235], v131
	v_cvt_pk_f32_fp8_sdwa v[130:131], v131 src0_sel:WORD_1
	v_pk_fma_f32 v[216:217], v[210:211], v[216:217], 0 op_sel_hi:[0,1,0]
	v_pk_fma_f32 v[226:227], v[210:211], v[226:227], 0 op_sel_hi:[0,1,0]
	v_pk_fma_f32 v[228:229], v[210:211], v[228:229], 0 op_sel_hi:[0,1,0]
	v_pk_fma_f32 v[128:129], v[210:211], v[128:129], 0 op_sel_hi:[0,1,0]
	v_pk_fma_f32 v[230:231], v[210:211], v[230:231], 0 op_sel_hi:[0,1,0]
	v_pk_fma_f32 v[232:233], v[210:211], v[232:233], 0 op_sel_hi:[0,1,0]
	v_pk_fma_f32 v[234:235], v[210:211], v[234:235], 0 op_sel_hi:[0,1,0]
	v_pk_fma_f32 v[130:131], v[210:211], v[130:131], 0 op_sel_hi:[0,1,0]
	v_mov_b32_e32 v132, v211
	s_waitcnt vmcnt(15)
	v_cvt_pk_f32_fp8_e32 v[210:211], v124
	v_cvt_pk_f32_fp8_sdwa v[236:237], v124 src0_sel:WORD_1
	v_cvt_pk_f32_fp8_e32 v[238:239], v125
	v_cvt_pk_f32_fp8_sdwa v[124:125], v125 src0_sel:WORD_1
	v_pk_fma_f32 v[210:211], v[132:133], v[210:211], v[216:217] op_sel_hi:[0,1,1]
	v_pk_fma_f32 v[216:217], v[132:133], v[236:237], v[226:227] op_sel_hi:[0,1,1]
	v_pk_fma_f32 v[226:227], v[132:133], v[238:239], v[228:229] op_sel_hi:[0,1,1]
	v_pk_fma_f32 v[124:125], v[132:133], v[124:125], v[128:129] op_sel_hi:[0,1,1]
	v_cvt_pk_f32_fp8_e32 v[128:129], v126
	v_cvt_pk_f32_fp8_sdwa v[228:229], v126 src0_sel:WORD_1
	v_cvt_pk_f32_fp8_e32 v[236:237], v127
	v_cvt_pk_f32_fp8_sdwa v[126:127], v127 src0_sel:WORD_1
	v_pk_fma_f32 v[128:129], v[132:133], v[128:129], v[230:231] op_sel_hi:[0,1,1]
	v_pk_fma_f32 v[228:229], v[132:133], v[228:229], v[232:233] op_sel_hi:[0,1,1]
	v_pk_fma_f32 v[230:231], v[132:133], v[236:237], v[234:235] op_sel_hi:[0,1,1]
	s_waitcnt vmcnt(14)
	v_cvt_pk_f32_fp8_e32 v[232:233], v120
	v_cvt_pk_f32_fp8_sdwa v[234:235], v120 src0_sel:WORD_1
	v_cvt_pk_f32_fp8_e32 v[236:237], v121
	v_cvt_pk_f32_fp8_sdwa v[120:121], v121 src0_sel:WORD_1
	v_pk_fma_f32 v[126:127], v[132:133], v[126:127], v[130:131] op_sel_hi:[0,1,1]
	v_pk_fma_f32 v[210:211], v[208:209], v[232:233], v[210:211] op_sel_hi:[0,1,1]
	v_pk_fma_f32 v[216:217], v[208:209], v[234:235], v[216:217] op_sel_hi:[0,1,1]
	v_pk_fma_f32 v[120:121], v[208:209], v[120:121], v[124:125] op_sel_hi:[0,1,1]
	v_cvt_pk_f32_fp8_e32 v[124:125], v122
	v_cvt_pk_f32_fp8_sdwa v[232:233], v122 src0_sel:WORD_1
	v_cvt_pk_f32_fp8_e32 v[234:235], v123
	v_cvt_pk_f32_fp8_sdwa v[122:123], v123 src0_sel:WORD_1
	v_pk_fma_f32 v[226:227], v[208:209], v[236:237], v[226:227] op_sel_hi:[0,1,1]
	v_pk_fma_f32 v[124:125], v[208:209], v[124:125], v[128:129] op_sel_hi:[0,1,1]
	v_pk_fma_f32 v[128:129], v[208:209], v[232:233], v[228:229] op_sel_hi:[0,1,1]
	v_pk_fma_f32 v[228:229], v[208:209], v[234:235], v[230:231] op_sel_hi:[0,1,1]
	v_pk_fma_f32 v[122:123], v[208:209], v[122:123], v[126:127] op_sel_hi:[0,1,1]
	v_mov_b32_e32 v126, v209
	s_waitcnt vmcnt(13)
	v_cvt_pk_f32_fp8_e32 v[130:131], v116
	v_cvt_pk_f32_fp8_sdwa v[208:209], v116 src0_sel:WORD_1
	v_cvt_pk_f32_fp8_e32 v[230:231], v117
	v_cvt_pk_f32_fp8_sdwa v[116:117], v117 src0_sel:WORD_1
	v_pk_fma_f32 v[130:131], v[126:127], v[130:131], v[210:211] op_sel_hi:[0,1,1]
	v_pk_fma_f32 v[208:209], v[126:127], v[208:209], v[216:217] op_sel_hi:[0,1,1]
	v_pk_fma_f32 v[210:211], v[126:127], v[230:231], v[226:227] op_sel_hi:[0,1,1]
	v_pk_fma_f32 v[116:117], v[126:127], v[116:117], v[120:121] op_sel_hi:[0,1,1]
	v_cvt_pk_f32_fp8_e32 v[120:121], v118
	v_cvt_pk_f32_fp8_sdwa v[216:217], v118 src0_sel:WORD_1
	v_cvt_pk_f32_fp8_e32 v[226:227], v119
	v_cvt_pk_f32_fp8_sdwa v[118:119], v119 src0_sel:WORD_1
	v_pk_fma_f32 v[120:121], v[126:127], v[120:121], v[124:125] op_sel_hi:[0,1,1]
	v_pk_fma_f32 v[124:125], v[126:127], v[216:217], v[128:129] op_sel_hi:[0,1,1]
	v_pk_fma_f32 v[128:129], v[126:127], v[226:227], v[228:229] op_sel_hi:[0,1,1]
	v_pk_fma_f32 v[118:119], v[126:127], v[118:119], v[122:123] op_sel_hi:[0,1,1]
	s_waitcnt vmcnt(12)
	v_cvt_pk_f32_fp8_e32 v[126:127], v112
	v_cvt_pk_f32_fp8_sdwa v[216:217], v112 src0_sel:WORD_1
	v_cvt_pk_f32_fp8_e32 v[226:227], v113
	v_cvt_pk_f32_fp8_sdwa v[112:113], v113 src0_sel:WORD_1
	v_pk_fma_f32 v[126:127], v[206:207], v[126:127], v[130:131] op_sel_hi:[0,1,1]
	v_pk_fma_f32 v[130:131], v[206:207], v[216:217], v[208:209] op_sel_hi:[0,1,1]
	v_pk_fma_f32 v[208:209], v[206:207], v[226:227], v[210:211] op_sel_hi:[0,1,1]
	v_pk_fma_f32 v[112:113], v[206:207], v[112:113], v[116:117] op_sel_hi:[0,1,1]
	v_cvt_pk_f32_fp8_e32 v[116:117], v114
	v_cvt_pk_f32_fp8_sdwa v[210:211], v114 src0_sel:WORD_1
	v_cvt_pk_f32_fp8_e32 v[216:217], v115
	v_cvt_pk_f32_fp8_sdwa v[114:115], v115 src0_sel:WORD_1
	v_pk_fma_f32 v[116:117], v[206:207], v[116:117], v[120:121] op_sel_hi:[0,1,1]
	v_pk_fma_f32 v[120:121], v[206:207], v[210:211], v[124:125] op_sel_hi:[0,1,1]
	v_pk_fma_f32 v[124:125], v[206:207], v[216:217], v[128:129] op_sel_hi:[0,1,1]
	v_pk_fma_f32 v[114:115], v[206:207], v[114:115], v[118:119] op_sel_hi:[0,1,1]
	v_mov_b32_e32 v118, v207
	s_waitcnt vmcnt(11)
; DI void up_math(const u32x4 (&W)[16], const u32 (&pj)[16], float* __restrict__ yrow, int lane) {
;   f2 y[8];
; #pragma unroll
;   for (int i = 0; i < 8; ++i) y[i] = f2{0.f, 0.f};
; #pragma unroll
;   for (int j = 0; j < 16; ++j) {
;     const float h = __uint_as_float(pj[j] << 16);
;     const f2 hh = {h, h};
; #pragma unroll
;     for (int d = 0; d < 4; ++d) {
;       f2 lo = __builtin_amdgcn_cvt_pk_f32_fp8((int)W[j][d], false);
;       f2 hi = __builtin_amdgcn_cvt_pk_f32_fp8((int)W[j][d], true);
;       y[2 * d] = lo * hh + y[2 * d];
;       y[2 * d + 1] = hi * hh + y[2 * d + 1];
;     }
;   }
	v_cvt_pk_f32_fp8_e32 v[122:123], v108
	v_cvt_pk_f32_fp8_sdwa v[128:129], v108 src0_sel:WORD_1
	v_cvt_pk_f32_fp8_e32 v[206:207], v109
	v_cvt_pk_f32_fp8_sdwa v[108:109], v109 src0_sel:WORD_1
	v_pk_fma_f32 v[122:123], v[118:119], v[122:123], v[126:127] op_sel_hi:[0,1,1]
	v_pk_fma_f32 v[126:127], v[118:119], v[128:129], v[130:131] op_sel_hi:[0,1,1]
	v_pk_fma_f32 v[128:129], v[118:119], v[206:207], v[208:209] op_sel_hi:[0,1,1]
	v_pk_fma_f32 v[108:109], v[118:119], v[108:109], v[112:113] op_sel_hi:[0,1,1]
	v_cvt_pk_f32_fp8_e32 v[112:113], v110
	v_cvt_pk_f32_fp8_sdwa v[130:131], v110 src0_sel:WORD_1
	v_cvt_pk_f32_fp8_e32 v[206:207], v111
	v_cvt_pk_f32_fp8_sdwa v[110:111], v111 src0_sel:WORD_1
	v_pk_fma_f32 v[112:113], v[118:119], v[112:113], v[116:117] op_sel_hi:[0,1,1]
	v_pk_fma_f32 v[116:117], v[118:119], v[130:131], v[120:121] op_sel_hi:[0,1,1]
	v_pk_fma_f32 v[120:121], v[118:119], v[206:207], v[124:125] op_sel_hi:[0,1,1]
	v_pk_fma_f32 v[110:111], v[118:119], v[110:111], v[114:115] op_sel_hi:[0,1,1]
	s_waitcnt vmcnt(10)
	v_cvt_pk_f32_fp8_e32 v[118:119], v104
	v_cvt_pk_f32_fp8_sdwa v[124:125], v104 src0_sel:WORD_1
	v_cvt_pk_f32_fp8_e32 v[130:131], v105
	v_cvt_pk_f32_fp8_sdwa v[104:105], v105 src0_sel:WORD_1
	v_pk_fma_f32 v[118:119], v[204:205], v[118:119], v[122:123] op_sel_hi:[0,1,1]
	v_pk_fma_f32 v[122:123], v[204:205], v[124:125], v[126:127] op_sel_hi:[0,1,1]
	v_pk_fma_f32 v[124:125], v[204:205], v[130:131], v[128:129] op_sel_hi:[0,1,1]
	v_pk_fma_f32 v[104:105], v[204:205], v[104:105], v[108:109] op_sel_hi:[0,1,1]
	v_cvt_pk_f32_fp8_e32 v[108:109], v106
	v_cvt_pk_f32_fp8_sdwa v[126:127], v106 src0_sel:WORD_1
	v_cvt_pk_f32_fp8_e32 v[128:129], v107
	v_cvt_pk_f32_fp8_sdwa v[106:107], v107 src0_sel:WORD_1
	v_pk_fma_f32 v[108:109], v[204:205], v[108:109], v[112:113] op_sel_hi:[0,1,1]
	v_pk_fma_f32 v[112:113], v[204:205], v[126:127], v[116:117] op_sel_hi:[0,1,1]
	v_pk_fma_f32 v[116:117], v[204:205], v[128:129], v[120:121] op_sel_hi:[0,1,1]
	v_pk_fma_f32 v[106:107], v[204:205], v[106:107], v[110:111] op_sel_hi:[0,1,1]
	s_waitcnt vmcnt(9)
	v_cvt_pk_f32_fp8_e32 v[114:115], v100
	v_cvt_pk_f32_fp8_sdwa v[120:121], v100 src0_sel:WORD_1
	v_cvt_pk_f32_fp8_e32 v[126:127], v101
	v_cvt_pk_f32_fp8_sdwa v[100:101], v101 src0_sel:WORD_1
	v_pk_fma_f32 v[114:115], v[204:205], v[114:115], v[118:119] op_sel:[1,0,0] op_sel_hi:[1,1,1]
	v_pk_fma_f32 v[118:119], v[204:205], v[120:121], v[122:123] op_sel:[1,0,0] op_sel_hi:[1,1,1]
	v_pk_fma_f32 v[120:121], v[204:205], v[126:127], v[124:125] op_sel:[1,0,0] op_sel_hi:[1,1,1]
	v_pk_fma_f32 v[100:101], v[204:205], v[100:101], v[104:105] op_sel:[1,0,0] op_sel_hi:[1,1,1]
	v_cvt_pk_f32_fp8_e32 v[104:105], v102
	v_cvt_pk_f32_fp8_sdwa v[122:123], v102 src0_sel:WORD_1
	v_cvt_pk_f32_fp8_e32 v[124:125], v103
	v_cvt_pk_f32_fp8_sdwa v[102:103], v103 src0_sel:WORD_1
	v_pk_fma_f32 v[104:105], v[204:205], v[104:105], v[108:109] op_sel:[1,0,0] op_sel_hi:[1,1,1]
	v_pk_fma_f32 v[108:109], v[204:205], v[122:123], v[112:113] op_sel:[1,0,0] op_sel_hi:[1,1,1]
	v_pk_fma_f32 v[112:113], v[204:205], v[124:125], v[116:117] op_sel:[1,0,0] op_sel_hi:[1,1,1]
	v_pk_fma_f32 v[102:103], v[204:205], v[102:103], v[106:107] op_sel:[1,0,0] op_sel_hi:[1,1,1]
	s_waitcnt vmcnt(8)
	v_cvt_pk_f32_fp8_e32 v[110:111], v96
	v_cvt_pk_f32_fp8_sdwa v[116:117], v96 src0_sel:WORD_1
	v_cvt_pk_f32_fp8_e32 v[122:123], v97
	v_cvt_pk_f32_fp8_sdwa v[96:97], v97 src0_sel:WORD_1
	v_pk_fma_f32 v[110:111], v[202:203], v[110:111], v[114:115] op_sel_hi:[0,1,1]
	v_pk_fma_f32 v[114:115], v[202:203], v[116:117], v[118:119] op_sel_hi:[0,1,1]
	v_pk_fma_f32 v[116:117], v[202:203], v[122:123], v[120:121] op_sel_hi:[0,1,1]
	v_pk_fma_f32 v[96:97], v[202:203], v[96:97], v[100:101] op_sel_hi:[0,1,1]
	v_cvt_pk_f32_fp8_e32 v[100:101], v98
	v_cvt_pk_f32_fp8_sdwa v[118:119], v98 src0_sel:WORD_1
	v_cvt_pk_f32_fp8_e32 v[120:121], v99
	v_cvt_pk_f32_fp8_sdwa v[98:99], v99 src0_sel:WORD_1
	v_pk_fma_f32 v[100:101], v[202:203], v[100:101], v[104:105] op_sel_hi:[0,1,1]
	v_pk_fma_f32 v[104:105], v[202:203], v[118:119], v[108:109] op_sel_hi:[0,1,1]
	v_pk_fma_f32 v[108:109], v[202:203], v[120:121], v[112:113] op_sel_hi:[0,1,1]
	v_pk_fma_f32 v[98:99], v[202:203], v[98:99], v[102:103] op_sel_hi:[0,1,1]
	s_waitcnt vmcnt(7)
	v_cvt_pk_f32_fp8_e32 v[106:107], v92
	v_cvt_pk_f32_fp8_sdwa v[112:113], v92 src0_sel:WORD_1
	v_cvt_pk_f32_fp8_e32 v[118:119], v93
	v_cvt_pk_f32_fp8_sdwa v[92:93], v93 src0_sel:WORD_1
	v_pk_fma_f32 v[106:107], v[202:203], v[106:107], v[110:111] op_sel:[1,0,0] op_sel_hi:[1,1,1]
	v_pk_fma_f32 v[110:111], v[202:203], v[112:113], v[114:115] op_sel:[1,0,0] op_sel_hi:[1,1,1]
	v_pk_fma_f32 v[112:113], v[202:203], v[118:119], v[116:117] op_sel:[1,0,0] op_sel_hi:[1,1,1]
	v_pk_fma_f32 v[92:93], v[202:203], v[92:93], v[96:97] op_sel:[1,0,0] op_sel_hi:[1,1,1]
	v_cvt_pk_f32_fp8_e32 v[96:97], v94
	v_cvt_pk_f32_fp8_sdwa v[114:115], v94 src0_sel:WORD_1
	v_cvt_pk_f32_fp8_e32 v[116:117], v95
	v_cvt_pk_f32_fp8_sdwa v[94:95], v95 src0_sel:WORD_1
	v_pk_fma_f32 v[96:97], v[202:203], v[96:97], v[100:101] op_sel:[1,0,0] op_sel_hi:[1,1,1]
	v_pk_fma_f32 v[100:101], v[202:203], v[114:115], v[104:105] op_sel:[1,0,0] op_sel_hi:[1,1,1]
	v_pk_fma_f32 v[104:105], v[202:203], v[116:117], v[108:109] op_sel:[1,0,0] op_sel_hi:[1,1,1]
	v_pk_fma_f32 v[94:95], v[202:203], v[94:95], v[98:99] op_sel:[1,0,0] op_sel_hi:[1,1,1]
	s_waitcnt vmcnt(6)
; DI void up_math(const u32x4 (&W)[16], const u32 (&pj)[16], float* __restrict__ yrow, int lane) {
;   f2 y[8];
; #pragma unroll
;   for (int i = 0; i < 8; ++i) y[i] = f2{0.f, 0.f};
; #pragma unroll
;   for (int j = 0; j < 16; ++j) {
;     const float h = __uint_as_float(pj[j] << 16);
;     const f2 hh = {h, h};
; #pragma unroll
;     for (int d = 0; d < 4; ++d) {
;       f2 lo = __builtin_amdgcn_cvt_pk_f32_fp8((int)W[j][d], false);
;       f2 hi = __builtin_amdgcn_cvt_pk_f32_fp8((int)W[j][d], true);
;       y[2 * d] = lo * hh + y[2 * d];
;       y[2 * d + 1] = hi * hh + y[2 * d + 1];
;     }
;   }
	v_cvt_pk_f32_fp8_e32 v[102:103], v88
	v_cvt_pk_f32_fp8_sdwa v[108:109], v88 src0_sel:WORD_1
	v_cvt_pk_f32_fp8_e32 v[114:115], v89
	v_cvt_pk_f32_fp8_sdwa v[88:89], v89 src0_sel:WORD_1
	v_pk_fma_f32 v[102:103], v[200:201], v[102:103], v[106:107] op_sel_hi:[0,1,1]
	v_pk_fma_f32 v[106:107], v[200:201], v[108:109], v[110:111] op_sel_hi:[0,1,1]
	v_pk_fma_f32 v[108:109], v[200:201], v[114:115], v[112:113] op_sel_hi:[0,1,1]
	v_pk_fma_f32 v[88:89], v[200:201], v[88:89], v[92:93] op_sel_hi:[0,1,1]
	v_cvt_pk_f32_fp8_e32 v[92:93], v90
	v_cvt_pk_f32_fp8_sdwa v[110:111], v90 src0_sel:WORD_1
	v_cvt_pk_f32_fp8_e32 v[112:113], v91
	v_cvt_pk_f32_fp8_sdwa v[90:91], v91 src0_sel:WORD_1
	v_pk_fma_f32 v[92:93], v[200:201], v[92:93], v[96:97] op_sel_hi:[0,1,1]
	v_pk_fma_f32 v[96:97], v[200:201], v[110:111], v[100:101] op_sel_hi:[0,1,1]
	v_pk_fma_f32 v[100:101], v[200:201], v[112:113], v[104:105] op_sel_hi:[0,1,1]
	v_pk_fma_f32 v[90:91], v[200:201], v[90:91], v[94:95] op_sel_hi:[0,1,1]
	s_waitcnt vmcnt(5)
	v_cvt_pk_f32_fp8_e32 v[98:99], v84
	v_cvt_pk_f32_fp8_sdwa v[104:105], v84 src0_sel:WORD_1
	v_cvt_pk_f32_fp8_e32 v[110:111], v85
	v_cvt_pk_f32_fp8_sdwa v[84:85], v85 src0_sel:WORD_1
	v_pk_fma_f32 v[98:99], v[200:201], v[98:99], v[102:103] op_sel:[1,0,0] op_sel_hi:[1,1,1]
	v_pk_fma_f32 v[102:103], v[200:201], v[104:105], v[106:107] op_sel:[1,0,0] op_sel_hi:[1,1,1]
	v_pk_fma_f32 v[104:105], v[200:201], v[110:111], v[108:109] op_sel:[1,0,0] op_sel_hi:[1,1,1]
	v_pk_fma_f32 v[84:85], v[200:201], v[84:85], v[88:89] op_sel:[1,0,0] op_sel_hi:[1,1,1]
	v_cvt_pk_f32_fp8_e32 v[88:89], v86
	v_cvt_pk_f32_fp8_sdwa v[106:107], v86 src0_sel:WORD_1
	v_cvt_pk_f32_fp8_e32 v[108:109], v87
	v_cvt_pk_f32_fp8_sdwa v[86:87], v87 src0_sel:WORD_1
	v_pk_fma_f32 v[88:89], v[200:201], v[88:89], v[92:93] op_sel:[1,0,0] op_sel_hi:[1,1,1]
	v_pk_fma_f32 v[92:93], v[200:201], v[106:107], v[96:97] op_sel:[1,0,0] op_sel_hi:[1,1,1]
	v_pk_fma_f32 v[96:97], v[200:201], v[108:109], v[100:101] op_sel:[1,0,0] op_sel_hi:[1,1,1]
	v_pk_fma_f32 v[86:87], v[200:201], v[86:87], v[90:91] op_sel:[1,0,0] op_sel_hi:[1,1,1]
	s_waitcnt vmcnt(4)
	v_cvt_pk_f32_fp8_e32 v[94:95], v80
	v_cvt_pk_f32_fp8_sdwa v[100:101], v80 src0_sel:WORD_1
	v_cvt_pk_f32_fp8_e32 v[106:107], v81
	v_cvt_pk_f32_fp8_sdwa v[80:81], v81 src0_sel:WORD_1
	v_pk_fma_f32 v[94:95], v[198:199], v[94:95], v[98:99] op_sel_hi:[0,1,1]
	v_pk_fma_f32 v[98:99], v[198:199], v[100:101], v[102:103] op_sel_hi:[0,1,1]
	v_pk_fma_f32 v[100:101], v[198:199], v[106:107], v[104:105] op_sel_hi:[0,1,1]
	v_pk_fma_f32 v[80:81], v[198:199], v[80:81], v[84:85] op_sel_hi:[0,1,1]
	v_cvt_pk_f32_fp8_e32 v[84:85], v82
	v_cvt_pk_f32_fp8_sdwa v[102:103], v82 src0_sel:WORD_1
	v_cvt_pk_f32_fp8_e32 v[104:105], v83
	v_cvt_pk_f32_fp8_sdwa v[82:83], v83 src0_sel:WORD_1
	v_pk_fma_f32 v[84:85], v[198:199], v[84:85], v[88:89] op_sel_hi:[0,1,1]
	v_pk_fma_f32 v[88:89], v[198:199], v[102:103], v[92:93] op_sel_hi:[0,1,1]
	v_pk_fma_f32 v[92:93], v[198:199], v[104:105], v[96:97] op_sel_hi:[0,1,1]
	v_pk_fma_f32 v[82:83], v[198:199], v[82:83], v[86:87] op_sel_hi:[0,1,1]
	s_waitcnt vmcnt(3)
	v_cvt_pk_f32_fp8_e32 v[90:91], v76
	v_cvt_pk_f32_fp8_sdwa v[96:97], v76 src0_sel:WORD_1
	v_cvt_pk_f32_fp8_e32 v[102:103], v77
	v_cvt_pk_f32_fp8_sdwa v[76:77], v77 src0_sel:WORD_1
	v_pk_fma_f32 v[90:91], v[198:199], v[90:91], v[94:95] op_sel:[1,0,0] op_sel_hi:[1,1,1]
	v_pk_fma_f32 v[94:95], v[198:199], v[96:97], v[98:99] op_sel:[1,0,0] op_sel_hi:[1,1,1]
	v_pk_fma_f32 v[96:97], v[198:199], v[102:103], v[100:101] op_sel:[1,0,0] op_sel_hi:[1,1,1]
	v_pk_fma_f32 v[76:77], v[198:199], v[76:77], v[80:81] op_sel:[1,0,0] op_sel_hi:[1,1,1]
	v_cvt_pk_f32_fp8_e32 v[80:81], v78
	v_cvt_pk_f32_fp8_sdwa v[98:99], v78 src0_sel:WORD_1
	v_cvt_pk_f32_fp8_e32 v[100:101], v79
	v_cvt_pk_f32_fp8_sdwa v[78:79], v79 src0_sel:WORD_1
	v_pk_fma_f32 v[80:81], v[198:199], v[80:81], v[84:85] op_sel:[1,0,0] op_sel_hi:[1,1,1]
	v_pk_fma_f32 v[84:85], v[198:199], v[98:99], v[88:89] op_sel:[1,0,0] op_sel_hi:[1,1,1]
	v_pk_fma_f32 v[88:89], v[198:199], v[100:101], v[92:93] op_sel:[1,0,0] op_sel_hi:[1,1,1]
	v_pk_fma_f32 v[78:79], v[198:199], v[78:79], v[82:83] op_sel:[1,0,0] op_sel_hi:[1,1,1]
	s_waitcnt vmcnt(2)
	v_cvt_pk_f32_fp8_e32 v[86:87], v72
	v_cvt_pk_f32_fp8_sdwa v[92:93], v72 src0_sel:WORD_1
	v_cvt_pk_f32_fp8_e32 v[98:99], v73
	v_cvt_pk_f32_fp8_sdwa v[72:73], v73 src0_sel:WORD_1
	v_pk_fma_f32 v[86:87], v[196:197], v[86:87], v[90:91] op_sel_hi:[0,1,1]
	v_pk_fma_f32 v[90:91], v[196:197], v[92:93], v[94:95] op_sel_hi:[0,1,1]
	v_pk_fma_f32 v[92:93], v[196:197], v[98:99], v[96:97] op_sel_hi:[0,1,1]
	v_pk_fma_f32 v[72:73], v[196:197], v[72:73], v[76:77] op_sel_hi:[0,1,1]
	v_cvt_pk_f32_fp8_e32 v[76:77], v74
	v_cvt_pk_f32_fp8_sdwa v[94:95], v74 src0_sel:WORD_1
	v_cvt_pk_f32_fp8_e32 v[96:97], v75
	v_cvt_pk_f32_fp8_sdwa v[74:75], v75 src0_sel:WORD_1
	v_pk_fma_f32 v[76:77], v[196:197], v[76:77], v[80:81] op_sel_hi:[0,1,1]
	v_pk_fma_f32 v[80:81], v[196:197], v[94:95], v[84:85] op_sel_hi:[0,1,1]
	v_pk_fma_f32 v[84:85], v[196:197], v[96:97], v[88:89] op_sel_hi:[0,1,1]
	v_pk_fma_f32 v[74:75], v[196:197], v[74:75], v[78:79] op_sel_hi:[0,1,1]
	s_waitcnt vmcnt(1)
; DI void up_issue(u32x4 (&W)[16], u32 (&pj)[16], const u32* pl, const unsigned char* wbase, int grp) {
; #pragma unroll
;   for (int j = 0; j < 16; ++j) {
;     pj[j] = pl[8 * j + grp];
;     W[j] = *(const u32x4*)(wbase + (size_t)(pj[j] >> 16) * 1024);
;   }
; DI void up_math(const u32x4 (&W)[16], const u32 (&pj)[16], float* __restrict__ yrow, int lane) {
;     ...
;   for (int j = 0; j < 16; ++j) {
;     const float h = __uint_as_float(pj[j] << 16);
;     const f2 hh = {h, h};
; #pragma unroll
;     for (int d = 0; d < 4; ++d) {
;       f2 lo = __builtin_amdgcn_cvt_pk_f32_fp8((int)W[j][d], false);
;       f2 hi = __builtin_amdgcn_cvt_pk_f32_fp8((int)W[j][d], true);
;       y[2 * d] = lo * hh + y[2 * d];
;       y[2 * d + 1] = hi * hh + y[2 * d + 1];
;     }
;   }
;   const bool b5 = lane & 32, b4 = lane & 16, b3 = lane & 8;
;   f2 q4[4];
; #pragma unroll
;   for (int i = 0; i < 4; ++i) {
;     f2 snd = b5 ? y[i] : y[i + 4]; f2 kp = b5 ? y[i + 4] : y[i];
;     q4[i] = f2{kp.x + __shfl_xor(snd.x, 32), kp.y + __shfl_xor(snd.y, 32)};
;   }
;   f2 r2[2];
; #pragma unroll
;   for (int i = 0; i < 2; ++i) {
;     f2 snd = b4 ? q4[i] : q4[i + 2]; f2 kp = b4 ? q4[i + 2] : q4[i];
;     r2[i] = f2{kp.x + __shfl_xor(snd.x, 16), kp.y + __shfl_xor(snd.y, 16)};
;   }
;   f2 a;
;   { f2 snd = b3 ? r2[0] : r2[1]; f2 kp = b3 ? r2[1] : r2[0]; a = f2{kp.x + __shfl_xor(snd.x, 8), kp.y + __shfl_xor(snd.y, 8)}; }
;   const int ci = (b5 ? 4 : 0) + (b4 ? 2 : 0) + (b3 ? 1 : 0);
;   *(float2*)(yrow + (lane & 7) * 16 + 2 * ci) = make_float2(a.x, a.y);
	v_cvt_pk_f32_fp8_e32 v[82:83], v68
	v_cvt_pk_f32_fp8_sdwa v[88:89], v68 src0_sel:WORD_1
	v_cvt_pk_f32_fp8_e32 v[94:95], v69
	v_cvt_pk_f32_fp8_sdwa v[68:69], v69 src0_sel:WORD_1
	v_pk_fma_f32 v[82:83], v[196:197], v[82:83], v[86:87] op_sel:[1,0,0] op_sel_hi:[1,1,1]
	v_pk_fma_f32 v[86:87], v[196:197], v[88:89], v[90:91] op_sel:[1,0,0] op_sel_hi:[1,1,1]
	v_pk_fma_f32 v[68:69], v[196:197], v[68:69], v[72:73] op_sel:[1,0,0] op_sel_hi:[1,1,1]
	v_cvt_pk_f32_fp8_e32 v[72:73], v70
	v_pk_fma_f32 v[88:89], v[196:197], v[94:95], v[92:93] op_sel:[1,0,0] op_sel_hi:[1,1,1]
	v_cvt_pk_f32_fp8_sdwa v[90:91], v70 src0_sel:WORD_1
	v_cvt_pk_f32_fp8_e32 v[92:93], v71
	v_cvt_pk_f32_fp8_sdwa v[70:71], v71 src0_sel:WORD_1
	v_pk_fma_f32 v[72:73], v[196:197], v[72:73], v[76:77] op_sel:[1,0,0] op_sel_hi:[1,1,1]
	v_pk_fma_f32 v[76:77], v[196:197], v[90:91], v[80:81] op_sel:[1,0,0] op_sel_hi:[1,1,1]
	v_pk_fma_f32 v[80:81], v[196:197], v[92:93], v[84:85] op_sel:[1,0,0] op_sel_hi:[1,1,1]
	v_pk_fma_f32 v[70:71], v[196:197], v[70:71], v[74:75] op_sel:[1,0,0] op_sel_hi:[1,1,1]
	s_nop 1
	v_permlane32_swap_b32_e32 v82, v72
	v_permlane32_swap_b32_e32 v83, v73
	v_permlane32_swap_b32_e32 v86, v76
	v_permlane32_swap_b32_e32 v87, v77
	v_permlane32_swap_b32_e32 v88, v80
	v_permlane32_swap_b32_e32 v89, v81
	v_permlane32_swap_b32_e32 v68, v70
	v_permlane32_swap_b32_e32 v69, v71
	v_pk_add_f32 v[72:73], v[82:83], v[72:73]
	v_pk_add_f32 v[74:75], v[86:87], v[76:77]
	v_pk_add_f32 v[76:77], v[88:89], v[80:81]
	v_pk_add_f32 v[68:69], v[68:69], v[70:71]
	s_nop 1
	v_permlane16_swap_b32_e32 v72, v76
	v_permlane16_swap_b32_e32 v73, v77
	v_permlane16_swap_b32_e32 v74, v68
	v_permlane16_swap_b32_e32 v75, v69
	v_pk_add_f32 v[70:71], v[72:73], v[76:77]
	v_pk_add_f32 v[68:69], v[74:75], v[68:69]
	s_nop 1
	v_add_f32_dpp v68, v68, v68 row_shr:8 row_mask:0xf bank_mask:0xc
	v_add_f32_dpp v69, v69, v69 row_shr:8 row_mask:0xf bank_mask:0xc
	v_add_f32_dpp v68, v70, v70 row_shl:8 row_mask:0xf bank_mask:0x3
	v_add_f32_dpp v69, v71, v71 row_shl:8 row_mask:0xf bank_mask:0x3
	v_add_co_u32_e32 v70, vcc, 0x1000, v188
	v_addc_co_u32_e32 v71, vcc, 0, v189, vcc
	global_store_dwordx2 v[70:71], v[68:69], off
	v_add_u32_e32 v145, 0x400, v145
	v_lshl_add_u64 v[188:189], v[188:189], 0, s[40:41]
	s_and_b64 vcc, exec, s[28:29]
	s_cbranch_vccnz .LBB0_814
.LBB0_827:
	v_mov_b32_e32 v210, 0
	v_mov_b32_e32 v211, 0
	v_mov_b32_e32 v208, 0
	v_mov_b32_e32 v209, 0
	v_mov_b32_e32 v206, 0
	v_mov_b32_e32 v207, 0
	ds_read_u16_d16_hi v210, v145
	ds_read_u16_d16_hi v211, v145 offset:32
	ds_read_u16_d16_hi v208, v145 offset:64
	ds_read_u16_d16_hi v209, v145 offset:96
	ds_read_u16_d16_hi v206, v145 offset:128
	ds_read_u16_d16_hi v207, v145 offset:160
	ds_read_u16_d16_hi v204, v145 offset:192
	ds_read_u16_d16_hi v205, v145 offset:224
	ds_read_u16_d16_hi v202, v145 offset:256
	ds_read_u16_d16_hi v203, v145 offset:288
	ds_read_u16_d16_hi v200, v145 offset:320
	ds_read_u16_d16_hi v201, v145 offset:352
	ds_read_u16_d16_hi v198, v145 offset:384
	ds_read_u16_d16_hi v199, v145 offset:416
	ds_read_u16_d16_hi v196, v145 offset:448
	ds_read_u16_d16_hi v197, v145 offset:480
	ds_read_u16 v128, v145 offset:2
	ds_read_u16 v124, v145 offset:34
	ds_read_u16 v120, v145 offset:66
	ds_read_u16 v116, v145 offset:98
	ds_read_u16 v112, v145 offset:130
	ds_read_u16 v108, v145 offset:162
	ds_read_u16 v104, v145 offset:194
	ds_read_u16 v100, v145 offset:226
	ds_read_u16 v96, v145 offset:258
	ds_read_u16 v92, v145 offset:290
	ds_read_u16 v88, v145 offset:322
	ds_read_u16 v84, v145 offset:354
	ds_read_u16 v80, v145 offset:386
	ds_read_u16 v76, v145 offset:418
	ds_read_u16 v72, v145 offset:450
	ds_read_u16 v68, v145 offset:482
	s_waitcnt lgkmcnt(15)
	v_lshl_add_u32 v128, v128, 10, v250
	global_load_dwordx4 v[128:131], v128, s[98:99]
	s_waitcnt lgkmcnt(14)
	v_lshl_add_u32 v124, v124, 10, v250
	global_load_dwordx4 v[124:127], v124, s[98:99]
	s_waitcnt lgkmcnt(13)
	v_lshl_add_u32 v120, v120, 10, v250
	global_load_dwordx4 v[120:123], v120, s[98:99]
	s_waitcnt lgkmcnt(12)
	v_lshl_add_u32 v116, v116, 10, v250
	global_load_dwordx4 v[116:119], v116, s[98:99]
	s_waitcnt lgkmcnt(11)
	v_lshl_add_u32 v112, v112, 10, v250
	global_load_dwordx4 v[112:115], v112, s[98:99]
	s_waitcnt lgkmcnt(10)
	v_lshl_add_u32 v108, v108, 10, v250
	global_load_dwordx4 v[108:111], v108, s[98:99]
	s_waitcnt lgkmcnt(9)
	v_lshl_add_u32 v104, v104, 10, v250
	global_load_dwordx4 v[104:107], v104, s[98:99]
	s_waitcnt lgkmcnt(8)
	v_lshl_add_u32 v100, v100, 10, v250
	global_load_dwordx4 v[100:103], v100, s[98:99]
	s_waitcnt lgkmcnt(7)
	v_lshl_add_u32 v96, v96, 10, v250
	global_load_dwordx4 v[96:99], v96, s[98:99]
	s_waitcnt lgkmcnt(6)
	v_lshl_add_u32 v92, v92, 10, v250
	global_load_dwordx4 v[92:95], v92, s[98:99]
	s_waitcnt lgkmcnt(5)
	v_lshl_add_u32 v88, v88, 10, v250
	global_load_dwordx4 v[88:91], v88, s[98:99]
	s_waitcnt lgkmcnt(4)
	v_lshl_add_u32 v84, v84, 10, v250
	global_load_dwordx4 v[84:87], v84, s[98:99]
	s_waitcnt lgkmcnt(3)
	v_lshl_add_u32 v80, v80, 10, v250
	global_load_dwordx4 v[80:83], v80, s[98:99]
	s_waitcnt lgkmcnt(2)
	v_lshl_add_u32 v76, v76, 10, v250
	global_load_dwordx4 v[76:79], v76, s[98:99]
	s_waitcnt lgkmcnt(1)
	v_lshl_add_u32 v72, v72, 10, v250
	global_load_dwordx4 v[72:75], v72, s[98:99]
	s_waitcnt lgkmcnt(0)
	v_lshl_add_u32 v68, v68, 10, v250
	global_load_dwordx4 v[68:71], v68, s[98:99]
	s_waitcnt vmcnt(31)
	v_cvt_pk_f32_fp8_e32 v[216:217], v4
	v_cvt_pk_f32_fp8_sdwa v[226:227], v4 src0_sel:WORD_1
	v_cvt_pk_f32_fp8_e32 v[228:229], v5
	v_cvt_pk_f32_fp8_sdwa v[230:231], v5 src0_sel:WORD_1
	v_cvt_pk_f32_fp8_e32 v[232:233], v6
	v_cvt_pk_f32_fp8_sdwa v[234:235], v6 src0_sel:WORD_1
	v_cvt_pk_f32_fp8_e32 v[236:237], v7
	v_cvt_pk_f32_fp8_sdwa v[238:239], v7 src0_sel:WORD_1
	s_waitcnt vmcnt(30)
; DI void up_math(const u32x4 (&W)[16], const u32 (&pj)[16], float* __restrict__ yrow, int lane) {
;   f2 y[8];
; #pragma unroll
;   for (int i = 0; i < 8; ++i) y[i] = f2{0.f, 0.f};
; #pragma unroll
;   for (int j = 0; j < 16; ++j) {
;     const float h = __uint_as_float(pj[j] << 16);
;     const f2 hh = {h, h};
; #pragma unroll
;     for (int d = 0; d < 4; ++d) {
;       f2 lo = __builtin_amdgcn_cvt_pk_f32_fp8((int)W[j][d], false);
;       f2 hi = __builtin_amdgcn_cvt_pk_f32_fp8((int)W[j][d], true);
;       y[2 * d] = lo * hh + y[2 * d];
;       y[2 * d + 1] = hi * hh + y[2 * d + 1];
;     }
;   }
	v_cvt_pk_f32_fp8_e32 v[240:241], v8
	v_cvt_pk_f32_fp8_sdwa v[242:243], v8 src0_sel:WORD_1
	v_cvt_pk_f32_fp8_e32 v[244:245], v9
	v_cvt_pk_f32_fp8_sdwa v[246:247], v9 src0_sel:WORD_1
	v_pk_fma_f32 v[216:217], v[178:179], v[216:217], 0 op_sel_hi:[0,1,0]
	v_pk_fma_f32 v[226:227], v[178:179], v[226:227], 0 op_sel_hi:[0,1,0]
	v_pk_fma_f32 v[228:229], v[178:179], v[228:229], 0 op_sel_hi:[0,1,0]
	v_pk_fma_f32 v[230:231], v[178:179], v[230:231], 0 op_sel_hi:[0,1,0]
	v_pk_fma_f32 v[232:233], v[178:179], v[232:233], 0 op_sel_hi:[0,1,0]
	v_pk_fma_f32 v[234:235], v[178:179], v[234:235], 0 op_sel_hi:[0,1,0]
	v_pk_fma_f32 v[236:237], v[178:179], v[236:237], 0 op_sel_hi:[0,1,0]
	v_pk_fma_f32 v[238:239], v[178:179], v[238:239], 0 op_sel_hi:[0,1,0]
	v_pk_fma_f32 v[216:217], v[178:179], v[240:241], v[216:217] op_sel:[1,0,0] op_sel_hi:[1,1,1]
	v_cvt_pk_f32_fp8_e32 v[240:241], v10
	v_pk_fma_f32 v[226:227], v[178:179], v[242:243], v[226:227] op_sel:[1,0,0] op_sel_hi:[1,1,1]
	v_pk_fma_f32 v[228:229], v[178:179], v[244:245], v[228:229] op_sel:[1,0,0] op_sel_hi:[1,1,1]
	v_pk_fma_f32 v[230:231], v[178:179], v[246:247], v[230:231] op_sel:[1,0,0] op_sel_hi:[1,1,1]
	v_cvt_pk_f32_fp8_sdwa v[242:243], v10 src0_sel:WORD_1
	v_cvt_pk_f32_fp8_e32 v[244:245], v11
	v_cvt_pk_f32_fp8_sdwa v[246:247], v11 src0_sel:WORD_1
	v_pk_fma_f32 v[232:233], v[178:179], v[240:241], v[232:233] op_sel:[1,0,0] op_sel_hi:[1,1,1]
	s_waitcnt vmcnt(29)
	v_cvt_pk_f32_fp8_e32 v[240:241], v12
	v_pk_fma_f32 v[234:235], v[178:179], v[242:243], v[234:235] op_sel:[1,0,0] op_sel_hi:[1,1,1]
	v_pk_fma_f32 v[236:237], v[178:179], v[244:245], v[236:237] op_sel:[1,0,0] op_sel_hi:[1,1,1]
	v_pk_fma_f32 v[238:239], v[178:179], v[246:247], v[238:239] op_sel:[1,0,0] op_sel_hi:[1,1,1]
	v_cvt_pk_f32_fp8_sdwa v[242:243], v12 src0_sel:WORD_1
	v_cvt_pk_f32_fp8_e32 v[244:245], v13
	v_cvt_pk_f32_fp8_sdwa v[246:247], v13 src0_sel:WORD_1
	v_pk_fma_f32 v[216:217], v[180:181], v[240:241], v[216:217] op_sel_hi:[0,1,1]
	v_cvt_pk_f32_fp8_e32 v[240:241], v14
	v_pk_fma_f32 v[226:227], v[180:181], v[242:243], v[226:227] op_sel_hi:[0,1,1]
	v_pk_fma_f32 v[228:229], v[180:181], v[244:245], v[228:229] op_sel_hi:[0,1,1]
	v_pk_fma_f32 v[230:231], v[180:181], v[246:247], v[230:231] op_sel_hi:[0,1,1]
	v_cvt_pk_f32_fp8_sdwa v[242:243], v14 src0_sel:WORD_1
	v_cvt_pk_f32_fp8_e32 v[244:245], v15
	v_cvt_pk_f32_fp8_sdwa v[246:247], v15 src0_sel:WORD_1
	v_pk_fma_f32 v[232:233], v[180:181], v[240:241], v[232:233] op_sel_hi:[0,1,1]
	s_waitcnt vmcnt(28)
	v_cvt_pk_f32_fp8_e32 v[240:241], v16
	v_pk_fma_f32 v[234:235], v[180:181], v[242:243], v[234:235] op_sel_hi:[0,1,1]
	v_pk_fma_f32 v[236:237], v[180:181], v[244:245], v[236:237] op_sel_hi:[0,1,1]
	v_pk_fma_f32 v[238:239], v[180:181], v[246:247], v[238:239] op_sel_hi:[0,1,1]
	v_cvt_pk_f32_fp8_sdwa v[242:243], v16 src0_sel:WORD_1
	v_cvt_pk_f32_fp8_e32 v[244:245], v17
	v_cvt_pk_f32_fp8_sdwa v[246:247], v17 src0_sel:WORD_1
	v_pk_fma_f32 v[216:217], v[180:181], v[240:241], v[216:217] op_sel:[1,0,0] op_sel_hi:[1,1,1]
	v_cvt_pk_f32_fp8_e32 v[240:241], v18
	v_pk_fma_f32 v[226:227], v[180:181], v[242:243], v[226:227] op_sel:[1,0,0] op_sel_hi:[1,1,1]
	v_pk_fma_f32 v[228:229], v[180:181], v[244:245], v[228:229] op_sel:[1,0,0] op_sel_hi:[1,1,1]
	v_pk_fma_f32 v[230:231], v[180:181], v[246:247], v[230:231] op_sel:[1,0,0] op_sel_hi:[1,1,1]
	v_cvt_pk_f32_fp8_sdwa v[242:243], v18 src0_sel:WORD_1
	v_cvt_pk_f32_fp8_e32 v[244:245], v19
	v_cvt_pk_f32_fp8_sdwa v[246:247], v19 src0_sel:WORD_1
	v_pk_fma_f32 v[232:233], v[180:181], v[240:241], v[232:233] op_sel:[1,0,0] op_sel_hi:[1,1,1]
	s_waitcnt vmcnt(27)
	v_cvt_pk_f32_fp8_e32 v[240:241], v20
	v_pk_fma_f32 v[234:235], v[180:181], v[242:243], v[234:235] op_sel:[1,0,0] op_sel_hi:[1,1,1]
	v_pk_fma_f32 v[236:237], v[180:181], v[244:245], v[236:237] op_sel:[1,0,0] op_sel_hi:[1,1,1]
	v_pk_fma_f32 v[238:239], v[180:181], v[246:247], v[238:239] op_sel:[1,0,0] op_sel_hi:[1,1,1]
	v_cvt_pk_f32_fp8_sdwa v[242:243], v20 src0_sel:WORD_1
	v_cvt_pk_f32_fp8_e32 v[244:245], v21
	v_cvt_pk_f32_fp8_sdwa v[246:247], v21 src0_sel:WORD_1
	v_pk_fma_f32 v[216:217], v[182:183], v[240:241], v[216:217] op_sel_hi:[0,1,1]
	v_cvt_pk_f32_fp8_e32 v[240:241], v22
	v_pk_fma_f32 v[226:227], v[182:183], v[242:243], v[226:227] op_sel_hi:[0,1,1]
	v_pk_fma_f32 v[228:229], v[182:183], v[244:245], v[228:229] op_sel_hi:[0,1,1]
	v_pk_fma_f32 v[230:231], v[182:183], v[246:247], v[230:231] op_sel_hi:[0,1,1]
	v_cvt_pk_f32_fp8_sdwa v[242:243], v22 src0_sel:WORD_1
	v_cvt_pk_f32_fp8_e32 v[244:245], v23
	v_cvt_pk_f32_fp8_sdwa v[246:247], v23 src0_sel:WORD_1
	v_pk_fma_f32 v[232:233], v[182:183], v[240:241], v[232:233] op_sel_hi:[0,1,1]
	s_waitcnt vmcnt(26)
	v_cvt_pk_f32_fp8_e32 v[240:241], v24
	v_pk_fma_f32 v[234:235], v[182:183], v[242:243], v[234:235] op_sel_hi:[0,1,1]
	v_pk_fma_f32 v[236:237], v[182:183], v[244:245], v[236:237] op_sel_hi:[0,1,1]
	v_pk_fma_f32 v[238:239], v[182:183], v[246:247], v[238:239] op_sel_hi:[0,1,1]
	v_cvt_pk_f32_fp8_sdwa v[242:243], v24 src0_sel:WORD_1
	v_cvt_pk_f32_fp8_e32 v[244:245], v25
	v_cvt_pk_f32_fp8_sdwa v[246:247], v25 src0_sel:WORD_1
	v_pk_fma_f32 v[216:217], v[182:183], v[240:241], v[216:217] op_sel:[1,0,0] op_sel_hi:[1,1,1]
	v_cvt_pk_f32_fp8_e32 v[240:241], v26
	v_pk_fma_f32 v[226:227], v[182:183], v[242:243], v[226:227] op_sel:[1,0,0] op_sel_hi:[1,1,1]
	v_pk_fma_f32 v[228:229], v[182:183], v[244:245], v[228:229] op_sel:[1,0,0] op_sel_hi:[1,1,1]
	v_pk_fma_f32 v[230:231], v[182:183], v[246:247], v[230:231] op_sel:[1,0,0] op_sel_hi:[1,1,1]
	v_cvt_pk_f32_fp8_sdwa v[242:243], v26 src0_sel:WORD_1
	v_cvt_pk_f32_fp8_e32 v[244:245], v27
	v_cvt_pk_f32_fp8_sdwa v[246:247], v27 src0_sel:WORD_1
	v_pk_fma_f32 v[232:233], v[182:183], v[240:241], v[232:233] op_sel:[1,0,0] op_sel_hi:[1,1,1]
	s_waitcnt vmcnt(25)
; DI void up_math(const u32x4 (&W)[16], const u32 (&pj)[16], float* __restrict__ yrow, int lane) {
;   f2 y[8];
; #pragma unroll
;   for (int i = 0; i < 8; ++i) y[i] = f2{0.f, 0.f};
; #pragma unroll
;   for (int j = 0; j < 16; ++j) {
;     const float h = __uint_as_float(pj[j] << 16);
;     const f2 hh = {h, h};
; #pragma unroll
;     for (int d = 0; d < 4; ++d) {
;       f2 lo = __builtin_amdgcn_cvt_pk_f32_fp8((int)W[j][d], false);
;       f2 hi = __builtin_amdgcn_cvt_pk_f32_fp8((int)W[j][d], true);
;       y[2 * d] = lo * hh + y[2 * d];
;       y[2 * d + 1] = hi * hh + y[2 * d + 1];
;     }
;   }
	v_cvt_pk_f32_fp8_e32 v[240:241], v28
	v_pk_fma_f32 v[234:235], v[182:183], v[242:243], v[234:235] op_sel:[1,0,0] op_sel_hi:[1,1,1]
	v_pk_fma_f32 v[236:237], v[182:183], v[244:245], v[236:237] op_sel:[1,0,0] op_sel_hi:[1,1,1]
	v_pk_fma_f32 v[238:239], v[182:183], v[246:247], v[238:239] op_sel:[1,0,0] op_sel_hi:[1,1,1]
	v_cvt_pk_f32_fp8_sdwa v[242:243], v28 src0_sel:WORD_1
	v_cvt_pk_f32_fp8_e32 v[244:245], v29
	v_cvt_pk_f32_fp8_sdwa v[246:247], v29 src0_sel:WORD_1
	v_pk_fma_f32 v[216:217], v[184:185], v[240:241], v[216:217] op_sel_hi:[0,1,1]
	v_cvt_pk_f32_fp8_e32 v[240:241], v30
	v_pk_fma_f32 v[226:227], v[184:185], v[242:243], v[226:227] op_sel_hi:[0,1,1]
	v_pk_fma_f32 v[228:229], v[184:185], v[244:245], v[228:229] op_sel_hi:[0,1,1]
	v_pk_fma_f32 v[230:231], v[184:185], v[246:247], v[230:231] op_sel_hi:[0,1,1]
	v_cvt_pk_f32_fp8_sdwa v[242:243], v30 src0_sel:WORD_1
	v_cvt_pk_f32_fp8_e32 v[244:245], v31
	v_cvt_pk_f32_fp8_sdwa v[246:247], v31 src0_sel:WORD_1
	v_pk_fma_f32 v[232:233], v[184:185], v[240:241], v[232:233] op_sel_hi:[0,1,1]
	s_waitcnt vmcnt(24)
	v_cvt_pk_f32_fp8_e32 v[240:241], v32
	v_pk_fma_f32 v[234:235], v[184:185], v[242:243], v[234:235] op_sel_hi:[0,1,1]
	v_pk_fma_f32 v[236:237], v[184:185], v[244:245], v[236:237] op_sel_hi:[0,1,1]
	v_pk_fma_f32 v[238:239], v[184:185], v[246:247], v[238:239] op_sel_hi:[0,1,1]
	v_cvt_pk_f32_fp8_sdwa v[242:243], v32 src0_sel:WORD_1
	v_cvt_pk_f32_fp8_e32 v[244:245], v33
	v_cvt_pk_f32_fp8_sdwa v[246:247], v33 src0_sel:WORD_1
	v_pk_fma_f32 v[216:217], v[184:185], v[240:241], v[216:217] op_sel:[1,0,0] op_sel_hi:[1,1,1]
	v_cvt_pk_f32_fp8_e32 v[240:241], v34
	v_pk_fma_f32 v[226:227], v[184:185], v[242:243], v[226:227] op_sel:[1,0,0] op_sel_hi:[1,1,1]
	v_pk_fma_f32 v[228:229], v[184:185], v[244:245], v[228:229] op_sel:[1,0,0] op_sel_hi:[1,1,1]
	v_pk_fma_f32 v[230:231], v[184:185], v[246:247], v[230:231] op_sel:[1,0,0] op_sel_hi:[1,1,1]
	v_cvt_pk_f32_fp8_sdwa v[242:243], v34 src0_sel:WORD_1
	v_cvt_pk_f32_fp8_e32 v[244:245], v35
	v_cvt_pk_f32_fp8_sdwa v[246:247], v35 src0_sel:WORD_1
	v_pk_fma_f32 v[232:233], v[184:185], v[240:241], v[232:233] op_sel:[1,0,0] op_sel_hi:[1,1,1]
	s_waitcnt vmcnt(23)
	v_cvt_pk_f32_fp8_e32 v[240:241], v36
	v_pk_fma_f32 v[234:235], v[184:185], v[242:243], v[234:235] op_sel:[1,0,0] op_sel_hi:[1,1,1]
	v_pk_fma_f32 v[236:237], v[184:185], v[244:245], v[236:237] op_sel:[1,0,0] op_sel_hi:[1,1,1]
	v_pk_fma_f32 v[238:239], v[184:185], v[246:247], v[238:239] op_sel:[1,0,0] op_sel_hi:[1,1,1]
	v_cvt_pk_f32_fp8_sdwa v[242:243], v36 src0_sel:WORD_1
	v_cvt_pk_f32_fp8_e32 v[244:245], v37
	v_cvt_pk_f32_fp8_sdwa v[246:247], v37 src0_sel:WORD_1
	v_pk_fma_f32 v[216:217], v[186:187], v[240:241], v[216:217] op_sel_hi:[0,1,1]
	v_cvt_pk_f32_fp8_e32 v[240:241], v38
	v_pk_fma_f32 v[226:227], v[186:187], v[242:243], v[226:227] op_sel_hi:[0,1,1]
	v_pk_fma_f32 v[228:229], v[186:187], v[244:245], v[228:229] op_sel_hi:[0,1,1]
	v_pk_fma_f32 v[230:231], v[186:187], v[246:247], v[230:231] op_sel_hi:[0,1,1]
	v_cvt_pk_f32_fp8_sdwa v[242:243], v38 src0_sel:WORD_1
	v_cvt_pk_f32_fp8_e32 v[244:245], v39
	v_cvt_pk_f32_fp8_sdwa v[246:247], v39 src0_sel:WORD_1
	v_pk_fma_f32 v[232:233], v[186:187], v[240:241], v[232:233] op_sel_hi:[0,1,1]
	s_waitcnt vmcnt(22)
	v_cvt_pk_f32_fp8_e32 v[240:241], v40
	v_pk_fma_f32 v[234:235], v[186:187], v[242:243], v[234:235] op_sel_hi:[0,1,1]
	v_pk_fma_f32 v[236:237], v[186:187], v[244:245], v[236:237] op_sel_hi:[0,1,1]
	v_pk_fma_f32 v[238:239], v[186:187], v[246:247], v[238:239] op_sel_hi:[0,1,1]
	v_cvt_pk_f32_fp8_sdwa v[242:243], v40 src0_sel:WORD_1
	v_cvt_pk_f32_fp8_e32 v[244:245], v41
	v_cvt_pk_f32_fp8_sdwa v[246:247], v41 src0_sel:WORD_1
	v_pk_fma_f32 v[216:217], v[186:187], v[240:241], v[216:217] op_sel:[1,0,0] op_sel_hi:[1,1,1]
	v_cvt_pk_f32_fp8_e32 v[240:241], v42
	v_pk_fma_f32 v[226:227], v[186:187], v[242:243], v[226:227] op_sel:[1,0,0] op_sel_hi:[1,1,1]
	v_pk_fma_f32 v[228:229], v[186:187], v[244:245], v[228:229] op_sel:[1,0,0] op_sel_hi:[1,1,1]
	v_pk_fma_f32 v[230:231], v[186:187], v[246:247], v[230:231] op_sel:[1,0,0] op_sel_hi:[1,1,1]
	v_cvt_pk_f32_fp8_sdwa v[242:243], v42 src0_sel:WORD_1
	v_cvt_pk_f32_fp8_e32 v[244:245], v43
	v_cvt_pk_f32_fp8_sdwa v[246:247], v43 src0_sel:WORD_1
	v_pk_fma_f32 v[232:233], v[186:187], v[240:241], v[232:233] op_sel:[1,0,0] op_sel_hi:[1,1,1]
	s_waitcnt vmcnt(21)
	v_cvt_pk_f32_fp8_e32 v[240:241], v44
	v_pk_fma_f32 v[234:235], v[186:187], v[242:243], v[234:235] op_sel:[1,0,0] op_sel_hi:[1,1,1]
	v_pk_fma_f32 v[236:237], v[186:187], v[244:245], v[236:237] op_sel:[1,0,0] op_sel_hi:[1,1,1]
	v_pk_fma_f32 v[238:239], v[186:187], v[246:247], v[238:239] op_sel:[1,0,0] op_sel_hi:[1,1,1]
	v_cvt_pk_f32_fp8_sdwa v[242:243], v44 src0_sel:WORD_1
	v_cvt_pk_f32_fp8_e32 v[244:245], v45
	v_cvt_pk_f32_fp8_sdwa v[246:247], v45 src0_sel:WORD_1
	v_pk_fma_f32 v[216:217], v[190:191], v[240:241], v[216:217] op_sel_hi:[0,1,1]
	v_cvt_pk_f32_fp8_e32 v[240:241], v46
	v_pk_fma_f32 v[226:227], v[190:191], v[242:243], v[226:227] op_sel_hi:[0,1,1]
	v_pk_fma_f32 v[228:229], v[190:191], v[244:245], v[228:229] op_sel_hi:[0,1,1]
	v_pk_fma_f32 v[230:231], v[190:191], v[246:247], v[230:231] op_sel_hi:[0,1,1]
	v_cvt_pk_f32_fp8_sdwa v[242:243], v46 src0_sel:WORD_1
	v_cvt_pk_f32_fp8_e32 v[244:245], v47
	v_cvt_pk_f32_fp8_sdwa v[246:247], v47 src0_sel:WORD_1
	v_pk_fma_f32 v[232:233], v[190:191], v[240:241], v[232:233] op_sel_hi:[0,1,1]
	s_waitcnt vmcnt(20)
; DI void up_math(const u32x4 (&W)[16], const u32 (&pj)[16], float* __restrict__ yrow, int lane) {
;     ...
;   for (int j = 0; j < 16; ++j) {
;     const float h = __uint_as_float(pj[j] << 16);
;     const f2 hh = {h, h};
; #pragma unroll
;     for (int d = 0; d < 4; ++d) {
;       f2 lo = __builtin_amdgcn_cvt_pk_f32_fp8((int)W[j][d], false);
;       f2 hi = __builtin_amdgcn_cvt_pk_f32_fp8((int)W[j][d], true);
;       y[2 * d] = lo * hh + y[2 * d];
;       y[2 * d + 1] = hi * hh + y[2 * d + 1];
;     }
;   }
;   const bool b5 = lane & 32, b4 = lane & 16, b3 = lane & 8;
;   f2 q4[4];
; #pragma unroll
;   for (int i = 0; i < 4; ++i) {
;     f2 snd = b5 ? y[i] : y[i + 4]; f2 kp = b5 ? y[i + 4] : y[i];
;     q4[i] = f2{kp.x + __shfl_xor(snd.x, 32), kp.y + __shfl_xor(snd.y, 32)};
;   }
;   f2 r2[2];
; #pragma unroll
;   for (int i = 0; i < 2; ++i) {
;     f2 snd = b4 ? q4[i] : q4[i + 2]; f2 kp = b4 ? q4[i + 2] : q4[i];
;     r2[i] = f2{kp.x + __shfl_xor(snd.x, 16), kp.y + __shfl_xor(snd.y, 16)};
;   }
;   f2 a;
;   { f2 snd = b3 ? r2[0] : r2[1]; f2 kp = b3 ? r2[1] : r2[0]; a = f2{kp.x + __shfl_xor(snd.x, 8), kp.y + __shfl_xor(snd.y, 8)}; }
;   const int ci = (b5 ? 4 : 0) + (b4 ? 2 : 0) + (b3 ? 1 : 0);
;   *(float2*)(yrow + (lane & 7) * 16 + 2 * ci) = make_float2(a.x, a.y);
	v_cvt_pk_f32_fp8_e32 v[240:241], v48
	v_pk_fma_f32 v[234:235], v[190:191], v[242:243], v[234:235] op_sel_hi:[0,1,1]
	v_pk_fma_f32 v[236:237], v[190:191], v[244:245], v[236:237] op_sel_hi:[0,1,1]
	v_pk_fma_f32 v[238:239], v[190:191], v[246:247], v[238:239] op_sel_hi:[0,1,1]
	v_cvt_pk_f32_fp8_sdwa v[242:243], v48 src0_sel:WORD_1
	v_cvt_pk_f32_fp8_e32 v[244:245], v49
	v_cvt_pk_f32_fp8_sdwa v[246:247], v49 src0_sel:WORD_1
	v_pk_fma_f32 v[216:217], v[190:191], v[240:241], v[216:217] op_sel:[1,0,0] op_sel_hi:[1,1,1]
	v_cvt_pk_f32_fp8_e32 v[240:241], v50
	v_pk_fma_f32 v[226:227], v[190:191], v[242:243], v[226:227] op_sel:[1,0,0] op_sel_hi:[1,1,1]
	v_pk_fma_f32 v[228:229], v[190:191], v[244:245], v[228:229] op_sel:[1,0,0] op_sel_hi:[1,1,1]
	v_pk_fma_f32 v[230:231], v[190:191], v[246:247], v[230:231] op_sel:[1,0,0] op_sel_hi:[1,1,1]
	v_cvt_pk_f32_fp8_sdwa v[242:243], v50 src0_sel:WORD_1
	v_cvt_pk_f32_fp8_e32 v[244:245], v51
	v_cvt_pk_f32_fp8_sdwa v[246:247], v51 src0_sel:WORD_1
	v_pk_fma_f32 v[232:233], v[190:191], v[240:241], v[232:233] op_sel:[1,0,0] op_sel_hi:[1,1,1]
	s_waitcnt vmcnt(19)
	v_cvt_pk_f32_fp8_e32 v[240:241], v52
	v_pk_fma_f32 v[234:235], v[190:191], v[242:243], v[234:235] op_sel:[1,0,0] op_sel_hi:[1,1,1]
	v_pk_fma_f32 v[236:237], v[190:191], v[244:245], v[236:237] op_sel:[1,0,0] op_sel_hi:[1,1,1]
	v_pk_fma_f32 v[238:239], v[190:191], v[246:247], v[238:239] op_sel:[1,0,0] op_sel_hi:[1,1,1]
	v_cvt_pk_f32_fp8_sdwa v[242:243], v52 src0_sel:WORD_1
	v_cvt_pk_f32_fp8_e32 v[244:245], v53
	v_cvt_pk_f32_fp8_sdwa v[246:247], v53 src0_sel:WORD_1
	v_pk_fma_f32 v[216:217], v[192:193], v[240:241], v[216:217] op_sel_hi:[0,1,1]
	v_cvt_pk_f32_fp8_e32 v[240:241], v54
	v_pk_fma_f32 v[226:227], v[192:193], v[242:243], v[226:227] op_sel_hi:[0,1,1]
	v_pk_fma_f32 v[228:229], v[192:193], v[244:245], v[228:229] op_sel_hi:[0,1,1]
	v_pk_fma_f32 v[230:231], v[192:193], v[246:247], v[230:231] op_sel_hi:[0,1,1]
	v_cvt_pk_f32_fp8_sdwa v[242:243], v54 src0_sel:WORD_1
	v_cvt_pk_f32_fp8_e32 v[244:245], v55
	v_cvt_pk_f32_fp8_sdwa v[246:247], v55 src0_sel:WORD_1
	v_pk_fma_f32 v[232:233], v[192:193], v[240:241], v[232:233] op_sel_hi:[0,1,1]
	s_waitcnt vmcnt(18)
	v_cvt_pk_f32_fp8_e32 v[240:241], v56
	v_pk_fma_f32 v[234:235], v[192:193], v[242:243], v[234:235] op_sel_hi:[0,1,1]
	v_pk_fma_f32 v[236:237], v[192:193], v[244:245], v[236:237] op_sel_hi:[0,1,1]
	v_pk_fma_f32 v[238:239], v[192:193], v[246:247], v[238:239] op_sel_hi:[0,1,1]
	v_cvt_pk_f32_fp8_sdwa v[242:243], v56 src0_sel:WORD_1
	v_cvt_pk_f32_fp8_e32 v[244:245], v57
	v_cvt_pk_f32_fp8_sdwa v[246:247], v57 src0_sel:WORD_1
	v_pk_fma_f32 v[216:217], v[192:193], v[240:241], v[216:217] op_sel:[1,0,0] op_sel_hi:[1,1,1]
	v_cvt_pk_f32_fp8_e32 v[240:241], v58
	v_pk_fma_f32 v[226:227], v[192:193], v[242:243], v[226:227] op_sel:[1,0,0] op_sel_hi:[1,1,1]
	v_pk_fma_f32 v[228:229], v[192:193], v[244:245], v[228:229] op_sel:[1,0,0] op_sel_hi:[1,1,1]
	v_pk_fma_f32 v[230:231], v[192:193], v[246:247], v[230:231] op_sel:[1,0,0] op_sel_hi:[1,1,1]
	v_cvt_pk_f32_fp8_sdwa v[242:243], v58 src0_sel:WORD_1
	v_cvt_pk_f32_fp8_e32 v[244:245], v59
	v_cvt_pk_f32_fp8_sdwa v[246:247], v59 src0_sel:WORD_1
	v_pk_fma_f32 v[232:233], v[192:193], v[240:241], v[232:233] op_sel:[1,0,0] op_sel_hi:[1,1,1]
	s_waitcnt vmcnt(17)
	v_cvt_pk_f32_fp8_e32 v[240:241], v60
	v_pk_fma_f32 v[234:235], v[192:193], v[242:243], v[234:235] op_sel:[1,0,0] op_sel_hi:[1,1,1]
	v_pk_fma_f32 v[236:237], v[192:193], v[244:245], v[236:237] op_sel:[1,0,0] op_sel_hi:[1,1,1]
	v_pk_fma_f32 v[238:239], v[192:193], v[246:247], v[238:239] op_sel:[1,0,0] op_sel_hi:[1,1,1]
	v_cvt_pk_f32_fp8_sdwa v[242:243], v60 src0_sel:WORD_1
	v_cvt_pk_f32_fp8_e32 v[244:245], v61
	v_cvt_pk_f32_fp8_sdwa v[246:247], v61 src0_sel:WORD_1
	v_pk_fma_f32 v[216:217], v[194:195], v[240:241], v[216:217] op_sel_hi:[0,1,1]
	v_cvt_pk_f32_fp8_e32 v[240:241], v62
	v_pk_fma_f32 v[226:227], v[194:195], v[242:243], v[226:227] op_sel_hi:[0,1,1]
	v_pk_fma_f32 v[228:229], v[194:195], v[244:245], v[228:229] op_sel_hi:[0,1,1]
	v_pk_fma_f32 v[230:231], v[194:195], v[246:247], v[230:231] op_sel_hi:[0,1,1]
	v_cvt_pk_f32_fp8_sdwa v[242:243], v62 src0_sel:WORD_1
	v_cvt_pk_f32_fp8_e32 v[244:245], v63
	v_cvt_pk_f32_fp8_sdwa v[246:247], v63 src0_sel:WORD_1
	v_pk_fma_f32 v[232:233], v[194:195], v[240:241], v[232:233] op_sel_hi:[0,1,1]
	s_waitcnt vmcnt(16)
	v_cvt_pk_f32_fp8_e32 v[240:241], v64
	v_pk_fma_f32 v[234:235], v[194:195], v[242:243], v[234:235] op_sel_hi:[0,1,1]
	v_pk_fma_f32 v[236:237], v[194:195], v[244:245], v[236:237] op_sel_hi:[0,1,1]
	v_pk_fma_f32 v[238:239], v[194:195], v[246:247], v[238:239] op_sel_hi:[0,1,1]
	v_cvt_pk_f32_fp8_sdwa v[242:243], v64 src0_sel:WORD_1
	v_cvt_pk_f32_fp8_e32 v[244:245], v65
	v_cvt_pk_f32_fp8_sdwa v[246:247], v65 src0_sel:WORD_1
	v_pk_fma_f32 v[216:217], v[194:195], v[240:241], v[216:217] op_sel:[1,0,0] op_sel_hi:[1,1,1]
	v_cvt_pk_f32_fp8_e32 v[240:241], v66
	v_pk_fma_f32 v[226:227], v[194:195], v[242:243], v[226:227] op_sel:[1,0,0] op_sel_hi:[1,1,1]
	v_pk_fma_f32 v[228:229], v[194:195], v[244:245], v[228:229] op_sel:[1,0,0] op_sel_hi:[1,1,1]
	v_pk_fma_f32 v[230:231], v[194:195], v[246:247], v[230:231] op_sel:[1,0,0] op_sel_hi:[1,1,1]
	v_cvt_pk_f32_fp8_sdwa v[242:243], v66 src0_sel:WORD_1
	v_cvt_pk_f32_fp8_e32 v[244:245], v67
	v_cvt_pk_f32_fp8_sdwa v[246:247], v67 src0_sel:WORD_1
	v_pk_fma_f32 v[232:233], v[194:195], v[240:241], v[232:233] op_sel:[1,0,0] op_sel_hi:[1,1,1]
	v_pk_fma_f32 v[234:235], v[194:195], v[242:243], v[234:235] op_sel:[1,0,0] op_sel_hi:[1,1,1]
	v_pk_fma_f32 v[236:237], v[194:195], v[244:245], v[236:237] op_sel:[1,0,0] op_sel_hi:[1,1,1]
	v_pk_fma_f32 v[238:239], v[194:195], v[246:247], v[238:239] op_sel:[1,0,0] op_sel_hi:[1,1,1]
	s_nop 1
	v_permlane32_swap_b32_e32 v216, v232
	v_permlane32_swap_b32_e32 v217, v233
	v_permlane32_swap_b32_e32 v228, v236
	v_permlane32_swap_b32_e32 v229, v237
	v_permlane32_swap_b32_e32 v226, v234
	v_permlane32_swap_b32_e32 v227, v235
	v_permlane32_swap_b32_e32 v230, v238
	v_permlane32_swap_b32_e32 v231, v239
	v_pk_add_f32 v[216:217], v[216:217], v[232:233]
	v_pk_add_f32 v[228:229], v[228:229], v[236:237]
	v_pk_add_f32 v[226:227], v[226:227], v[234:235]
	v_pk_add_f32 v[230:231], v[230:231], v[238:239]
	s_nop 1
	v_permlane16_swap_b32_e32 v216, v228
	v_permlane16_swap_b32_e32 v217, v229
	v_permlane16_swap_b32_e32 v226, v230
	v_permlane16_swap_b32_e32 v227, v231
	v_pk_add_f32 v[216:217], v[216:217], v[228:229]
	v_pk_add_f32 v[226:227], v[226:227], v[230:231]
	s_nop 1
	v_add_f32_dpp v216, v216, v216 row_shl:8 row_mask:0xf bank_mask:0x3
	v_add_f32_dpp v217, v217, v217 row_shl:8 row_mask:0xf bank_mask:0x3
	v_add_f32_dpp v216, v226, v226 row_shr:8 row_mask:0xf bank_mask:0xc
	v_add_f32_dpp v217, v227, v227 row_shr:8 row_mask:0xf bank_mask:0xc
	global_store_dwordx2 v[188:189], v[216:217], off
	s_cmp_gt_u32 s44, 13
	s_cselect_b64 s[28:29], -1, 0
	s_and_b64 vcc, exec, s[28:29]
	s_cbranch_vccnz .LBB0_826
; DI void up_issue(u32x4 (&W)[16], u32 (&pj)[16], const u32* pl, const unsigned char* wbase, int grp) {
; #pragma unroll
;   for (int j = 0; j < 16; ++j) {
;     pj[j] = pl[8 * j + grp];
;     W[j] = *(const u32x4*)(wbase + (size_t)(pj[j] >> 16) * 1024);
;   }
; DI void peer_up_phase(const Params& p, unsigned char* smem, int layer, u32* ctr) {
;     ...
;       for (int tl = 0; tl < 16; tl += 2) {
;         up_issue(WB, pB, pl + (tl + 1) * 128, wbase, grp);
;         __builtin_amdgcn_sched_barrier(0);
;         up_math(WA, pA, ybase + (size_t)tl * 1024, lane);
;         __builtin_amdgcn_sched_barrier(0);
;         if (tl + 2 < 16) up_issue(WA, pA, pl + (tl + 2) * 128, wbase, grp);
;         __builtin_amdgcn_sched_barrier(0);
;         up_math(WB, pB, ybase + (size_t)(tl + 1) * 1024, lane);
	ds_read_u16_d16_hi v178, v145 offset:512
	ds_read_u16_d16_hi v179, v145 offset:544
	ds_read_u16_d16_hi v180, v145 offset:576
	ds_read_u16_d16_hi v181, v145 offset:608
	ds_read_u16_d16_hi v182, v145 offset:640
	ds_read_u16_d16_hi v183, v145 offset:672
	ds_read_u16_d16_hi v184, v145 offset:704
	ds_read_u16_d16_hi v185, v145 offset:736
	ds_read_u16_d16_hi v186, v145 offset:768
	ds_read_u16_d16_hi v187, v145 offset:800
	ds_read_u16_d16_hi v190, v145 offset:832
	ds_read_u16_d16_hi v191, v145 offset:864
	ds_read_u16_d16_hi v192, v145 offset:896
	ds_read_u16_d16_hi v193, v145 offset:928
	ds_read_u16_d16_hi v194, v145 offset:960
	ds_read_u16_d16_hi v195, v145 offset:992
	ds_read_u16 v4, v145 offset:514
	ds_read_u16 v8, v145 offset:546
	ds_read_u16 v12, v145 offset:578
	ds_read_u16 v16, v145 offset:610
	ds_read_u16 v20, v145 offset:642
	ds_read_u16 v24, v145 offset:674
	ds_read_u16 v28, v145 offset:706
	ds_read_u16 v32, v145 offset:738
	ds_read_u16 v36, v145 offset:770
	ds_read_u16 v40, v145 offset:802
	ds_read_u16 v44, v145 offset:834
	ds_read_u16 v48, v145 offset:866
	ds_read_u16 v52, v145 offset:898
	ds_read_u16 v56, v145 offset:930
	ds_read_u16 v60, v145 offset:962
	ds_read_u16 v64, v145 offset:994
	s_waitcnt lgkmcnt(15)
	v_lshl_add_u32 v4, v4, 10, v250
	global_load_dwordx4 v[4:7], v4, s[98:99]
	s_waitcnt lgkmcnt(14)
	v_lshl_add_u32 v8, v8, 10, v250
	global_load_dwordx4 v[8:11], v8, s[98:99]
	s_waitcnt lgkmcnt(13)
	v_lshl_add_u32 v12, v12, 10, v250
	global_load_dwordx4 v[12:15], v12, s[98:99]
	s_waitcnt lgkmcnt(12)
	v_lshl_add_u32 v16, v16, 10, v250
	global_load_dwordx4 v[16:19], v16, s[98:99]
	s_waitcnt lgkmcnt(11)
	v_lshl_add_u32 v20, v20, 10, v250
	global_load_dwordx4 v[20:23], v20, s[98:99]
	s_waitcnt lgkmcnt(10)
	v_lshl_add_u32 v24, v24, 10, v250
	global_load_dwordx4 v[24:27], v24, s[98:99]
	s_waitcnt lgkmcnt(9)
	v_lshl_add_u32 v28, v28, 10, v250
	global_load_dwordx4 v[28:31], v28, s[98:99]
	s_waitcnt lgkmcnt(8)
	v_lshl_add_u32 v32, v32, 10, v250
	global_load_dwordx4 v[32:35], v32, s[98:99]
	s_waitcnt lgkmcnt(7)
	v_lshl_add_u32 v36, v36, 10, v250
	global_load_dwordx4 v[36:39], v36, s[98:99]
	s_waitcnt lgkmcnt(6)
	v_lshl_add_u32 v40, v40, 10, v250
	global_load_dwordx4 v[40:43], v40, s[98:99]
	s_waitcnt lgkmcnt(5)
	v_lshl_add_u32 v44, v44, 10, v250
	global_load_dwordx4 v[44:47], v44, s[98:99]
	s_waitcnt lgkmcnt(4)
	v_lshl_add_u32 v48, v48, 10, v250
	global_load_dwordx4 v[48:51], v48, s[98:99]
	s_waitcnt lgkmcnt(3)
	v_lshl_add_u32 v52, v52, 10, v250
	global_load_dwordx4 v[52:55], v52, s[98:99]
	s_waitcnt lgkmcnt(2)
	v_lshl_add_u32 v56, v56, 10, v250
	global_load_dwordx4 v[56:59], v56, s[98:99]
	s_waitcnt lgkmcnt(1)
	v_lshl_add_u32 v60, v60, 10, v250
	global_load_dwordx4 v[60:63], v60, s[98:99]
	s_waitcnt lgkmcnt(0)
	v_lshl_add_u32 v64, v64, 10, v250
	global_load_dwordx4 v[64:67], v64, s[98:99]
	s_branch .LBB0_826

; DI void up_math(const u32x4 (&W)[16], const u32 (&pj)[16], float* __restrict__ yrow, int lane) {
;   f2 y[8];
; #pragma unroll
;   for (int i = 0; i < 8; ++i) y[i] = f2{0.f, 0.f};
; #pragma unroll
;   for (int j = 0; j < 16; ++j) {
;     const float h = __uint_as_float(pj[j] << 16);
;     const f2 hh = {h, h};
; #pragma unroll
;     for (int d = 0; d < 4; ++d) {
;       f2 lo = __builtin_amdgcn_cvt_pk_f32_fp8((int)W[j][d], false);
;       f2 hi = __builtin_amdgcn_cvt_pk_f32_fp8((int)W[j][d], true);
;       y[2 * d] = lo * hh + y[2 * d];
;       y[2 * d + 1] = hi * hh + y[2 * d + 1];
;     }
;   }
.LBB0_1649:
	s_add_i32 s36, s36, 2
	s_waitcnt vmcnt(16)
	v_cvt_pk_f32_fp8_e32 v[216:217], v128
	v_cvt_pk_f32_fp8_sdwa v[226:227], v128 src0_sel:WORD_1
	v_cvt_pk_f32_fp8_e32 v[228:229], v129
	v_cvt_pk_f32_fp8_sdwa v[128:129], v129 src0_sel:WORD_1
	v_cvt_pk_f32_fp8_e32 v[230:231], v130
	v_cvt_pk_f32_fp8_sdwa v[232:233], v130 src0_sel:WORD_1
	v_cvt_pk_f32_fp8_e32 v[234:235], v131
	v_cvt_pk_f32_fp8_sdwa v[130:131], v131 src0_sel:WORD_1
	v_pk_fma_f32 v[216:217], v[210:211], v[216:217], 0 op_sel_hi:[0,1,0]
	v_pk_fma_f32 v[226:227], v[210:211], v[226:227], 0 op_sel_hi:[0,1,0]
	v_pk_fma_f32 v[228:229], v[210:211], v[228:229], 0 op_sel_hi:[0,1,0]
	v_pk_fma_f32 v[128:129], v[210:211], v[128:129], 0 op_sel_hi:[0,1,0]
	v_pk_fma_f32 v[230:231], v[210:211], v[230:231], 0 op_sel_hi:[0,1,0]
	v_pk_fma_f32 v[232:233], v[210:211], v[232:233], 0 op_sel_hi:[0,1,0]
	v_pk_fma_f32 v[234:235], v[210:211], v[234:235], 0 op_sel_hi:[0,1,0]
	v_pk_fma_f32 v[130:131], v[210:211], v[130:131], 0 op_sel_hi:[0,1,0]
	v_mov_b32_e32 v132, v211
	s_waitcnt vmcnt(15)
	v_cvt_pk_f32_fp8_e32 v[210:211], v124
	v_cvt_pk_f32_fp8_sdwa v[236:237], v124 src0_sel:WORD_1
	v_cvt_pk_f32_fp8_e32 v[238:239], v125
	v_cvt_pk_f32_fp8_sdwa v[124:125], v125 src0_sel:WORD_1
	v_pk_fma_f32 v[210:211], v[132:133], v[210:211], v[216:217] op_sel_hi:[0,1,1]
	v_pk_fma_f32 v[216:217], v[132:133], v[236:237], v[226:227] op_sel_hi:[0,1,1]
	v_pk_fma_f32 v[226:227], v[132:133], v[238:239], v[228:229] op_sel_hi:[0,1,1]
	v_pk_fma_f32 v[124:125], v[132:133], v[124:125], v[128:129] op_sel_hi:[0,1,1]
	v_cvt_pk_f32_fp8_e32 v[128:129], v126
	v_cvt_pk_f32_fp8_sdwa v[228:229], v126 src0_sel:WORD_1
	v_cvt_pk_f32_fp8_e32 v[236:237], v127
	v_cvt_pk_f32_fp8_sdwa v[126:127], v127 src0_sel:WORD_1
	v_pk_fma_f32 v[128:129], v[132:133], v[128:129], v[230:231] op_sel_hi:[0,1,1]
	v_pk_fma_f32 v[228:229], v[132:133], v[228:229], v[232:233] op_sel_hi:[0,1,1]
	v_pk_fma_f32 v[230:231], v[132:133], v[236:237], v[234:235] op_sel_hi:[0,1,1]
	s_waitcnt vmcnt(14)
	v_cvt_pk_f32_fp8_e32 v[232:233], v120
	v_cvt_pk_f32_fp8_sdwa v[234:235], v120 src0_sel:WORD_1
	v_cvt_pk_f32_fp8_e32 v[236:237], v121
	v_cvt_pk_f32_fp8_sdwa v[120:121], v121 src0_sel:WORD_1
	v_pk_fma_f32 v[126:127], v[132:133], v[126:127], v[130:131] op_sel_hi:[0,1,1]
	v_pk_fma_f32 v[210:211], v[208:209], v[232:233], v[210:211] op_sel_hi:[0,1,1]
	v_pk_fma_f32 v[216:217], v[208:209], v[234:235], v[216:217] op_sel_hi:[0,1,1]
	v_pk_fma_f32 v[120:121], v[208:209], v[120:121], v[124:125] op_sel_hi:[0,1,1]
	v_cvt_pk_f32_fp8_e32 v[124:125], v122
	v_cvt_pk_f32_fp8_sdwa v[232:233], v122 src0_sel:WORD_1
	v_cvt_pk_f32_fp8_e32 v[234:235], v123
	v_cvt_pk_f32_fp8_sdwa v[122:123], v123 src0_sel:WORD_1
	v_pk_fma_f32 v[226:227], v[208:209], v[236:237], v[226:227] op_sel_hi:[0,1,1]
	v_pk_fma_f32 v[124:125], v[208:209], v[124:125], v[128:129] op_sel_hi:[0,1,1]
	v_pk_fma_f32 v[128:129], v[208:209], v[232:233], v[228:229] op_sel_hi:[0,1,1]
	v_pk_fma_f32 v[228:229], v[208:209], v[234:235], v[230:231] op_sel_hi:[0,1,1]
	v_pk_fma_f32 v[122:123], v[208:209], v[122:123], v[126:127] op_sel_hi:[0,1,1]
	v_mov_b32_e32 v126, v209
	s_waitcnt vmcnt(13)
	v_cvt_pk_f32_fp8_e32 v[130:131], v116
	v_cvt_pk_f32_fp8_sdwa v[208:209], v116 src0_sel:WORD_1
	v_cvt_pk_f32_fp8_e32 v[230:231], v117
	v_cvt_pk_f32_fp8_sdwa v[116:117], v117 src0_sel:WORD_1
	v_pk_fma_f32 v[130:131], v[126:127], v[130:131], v[210:211] op_sel_hi:[0,1,1]
	v_pk_fma_f32 v[208:209], v[126:127], v[208:209], v[216:217] op_sel_hi:[0,1,1]
	v_pk_fma_f32 v[210:211], v[126:127], v[230:231], v[226:227] op_sel_hi:[0,1,1]
	v_pk_fma_f32 v[116:117], v[126:127], v[116:117], v[120:121] op_sel_hi:[0,1,1]
	v_cvt_pk_f32_fp8_e32 v[120:121], v118
	v_cvt_pk_f32_fp8_sdwa v[216:217], v118 src0_sel:WORD_1
	v_cvt_pk_f32_fp8_e32 v[226:227], v119
	v_cvt_pk_f32_fp8_sdwa v[118:119], v119 src0_sel:WORD_1
	v_pk_fma_f32 v[120:121], v[126:127], v[120:121], v[124:125] op_sel_hi:[0,1,1]
	v_pk_fma_f32 v[124:125], v[126:127], v[216:217], v[128:129] op_sel_hi:[0,1,1]
	v_pk_fma_f32 v[128:129], v[126:127], v[226:227], v[228:229] op_sel_hi:[0,1,1]
	v_pk_fma_f32 v[118:119], v[126:127], v[118:119], v[122:123] op_sel_hi:[0,1,1]
	s_waitcnt vmcnt(12)
	v_cvt_pk_f32_fp8_e32 v[126:127], v112
	v_cvt_pk_f32_fp8_sdwa v[216:217], v112 src0_sel:WORD_1
	v_cvt_pk_f32_fp8_e32 v[226:227], v113
	v_cvt_pk_f32_fp8_sdwa v[112:113], v113 src0_sel:WORD_1
	v_pk_fma_f32 v[126:127], v[206:207], v[126:127], v[130:131] op_sel_hi:[0,1,1]
	v_pk_fma_f32 v[130:131], v[206:207], v[216:217], v[208:209] op_sel_hi:[0,1,1]
	v_pk_fma_f32 v[208:209], v[206:207], v[226:227], v[210:211] op_sel_hi:[0,1,1]
	v_pk_fma_f32 v[112:113], v[206:207], v[112:113], v[116:117] op_sel_hi:[0,1,1]
	v_cvt_pk_f32_fp8_e32 v[116:117], v114
	v_cvt_pk_f32_fp8_sdwa v[210:211], v114 src0_sel:WORD_1
	v_cvt_pk_f32_fp8_e32 v[216:217], v115
	v_cvt_pk_f32_fp8_sdwa v[114:115], v115 src0_sel:WORD_1
	v_pk_fma_f32 v[116:117], v[206:207], v[116:117], v[120:121] op_sel_hi:[0,1,1]
	v_pk_fma_f32 v[120:121], v[206:207], v[210:211], v[124:125] op_sel_hi:[0,1,1]
	v_pk_fma_f32 v[124:125], v[206:207], v[216:217], v[128:129] op_sel_hi:[0,1,1]
	v_pk_fma_f32 v[114:115], v[206:207], v[114:115], v[118:119] op_sel_hi:[0,1,1]
	v_mov_b32_e32 v118, v207
	s_waitcnt vmcnt(11)
; DI void up_math(const u32x4 (&W)[16], const u32 (&pj)[16], float* __restrict__ yrow, int lane) {
;   f2 y[8];
; #pragma unroll
;   for (int i = 0; i < 8; ++i) y[i] = f2{0.f, 0.f};
; #pragma unroll
;   for (int j = 0; j < 16; ++j) {
;     const float h = __uint_as_float(pj[j] << 16);
;     const f2 hh = {h, h};
; #pragma unroll
;     for (int d = 0; d < 4; ++d) {
;       f2 lo = __builtin_amdgcn_cvt_pk_f32_fp8((int)W[j][d], false);
;       f2 hi = __builtin_amdgcn_cvt_pk_f32_fp8((int)W[j][d], true);
;       y[2 * d] = lo * hh + y[2 * d];
;       y[2 * d + 1] = hi * hh + y[2 * d + 1];
;     }
;   }
	v_cvt_pk_f32_fp8_e32 v[122:123], v108
	v_cvt_pk_f32_fp8_sdwa v[128:129], v108 src0_sel:WORD_1
	v_cvt_pk_f32_fp8_e32 v[206:207], v109
	v_cvt_pk_f32_fp8_sdwa v[108:109], v109 src0_sel:WORD_1
	v_pk_fma_f32 v[122:123], v[118:119], v[122:123], v[126:127] op_sel_hi:[0,1,1]
	v_pk_fma_f32 v[126:127], v[118:119], v[128:129], v[130:131] op_sel_hi:[0,1,1]
	v_pk_fma_f32 v[128:129], v[118:119], v[206:207], v[208:209] op_sel_hi:[0,1,1]
	v_pk_fma_f32 v[108:109], v[118:119], v[108:109], v[112:113] op_sel_hi:[0,1,1]
	v_cvt_pk_f32_fp8_e32 v[112:113], v110
	v_cvt_pk_f32_fp8_sdwa v[130:131], v110 src0_sel:WORD_1
	v_cvt_pk_f32_fp8_e32 v[206:207], v111
	v_cvt_pk_f32_fp8_sdwa v[110:111], v111 src0_sel:WORD_1
	v_pk_fma_f32 v[112:113], v[118:119], v[112:113], v[116:117] op_sel_hi:[0,1,1]
	v_pk_fma_f32 v[116:117], v[118:119], v[130:131], v[120:121] op_sel_hi:[0,1,1]
	v_pk_fma_f32 v[120:121], v[118:119], v[206:207], v[124:125] op_sel_hi:[0,1,1]
	v_pk_fma_f32 v[110:111], v[118:119], v[110:111], v[114:115] op_sel_hi:[0,1,1]
	s_waitcnt vmcnt(10)
	v_cvt_pk_f32_fp8_e32 v[118:119], v104
	v_cvt_pk_f32_fp8_sdwa v[124:125], v104 src0_sel:WORD_1
	v_cvt_pk_f32_fp8_e32 v[130:131], v105
	v_cvt_pk_f32_fp8_sdwa v[104:105], v105 src0_sel:WORD_1
	v_pk_fma_f32 v[118:119], v[204:205], v[118:119], v[122:123] op_sel_hi:[0,1,1]
	v_pk_fma_f32 v[122:123], v[204:205], v[124:125], v[126:127] op_sel_hi:[0,1,1]
	v_pk_fma_f32 v[124:125], v[204:205], v[130:131], v[128:129] op_sel_hi:[0,1,1]
	v_pk_fma_f32 v[104:105], v[204:205], v[104:105], v[108:109] op_sel_hi:[0,1,1]
	v_cvt_pk_f32_fp8_e32 v[108:109], v106
	v_cvt_pk_f32_fp8_sdwa v[126:127], v106 src0_sel:WORD_1
	v_cvt_pk_f32_fp8_e32 v[128:129], v107
	v_cvt_pk_f32_fp8_sdwa v[106:107], v107 src0_sel:WORD_1
	v_pk_fma_f32 v[108:109], v[204:205], v[108:109], v[112:113] op_sel_hi:[0,1,1]
	v_pk_fma_f32 v[112:113], v[204:205], v[126:127], v[116:117] op_sel_hi:[0,1,1]
	v_pk_fma_f32 v[116:117], v[204:205], v[128:129], v[120:121] op_sel_hi:[0,1,1]
	v_pk_fma_f32 v[106:107], v[204:205], v[106:107], v[110:111] op_sel_hi:[0,1,1]
	s_waitcnt vmcnt(9)
	v_cvt_pk_f32_fp8_e32 v[114:115], v100
	v_cvt_pk_f32_fp8_sdwa v[120:121], v100 src0_sel:WORD_1
	v_cvt_pk_f32_fp8_e32 v[126:127], v101
	v_cvt_pk_f32_fp8_sdwa v[100:101], v101 src0_sel:WORD_1
	v_pk_fma_f32 v[114:115], v[204:205], v[114:115], v[118:119] op_sel:[1,0,0] op_sel_hi:[1,1,1]
	v_pk_fma_f32 v[118:119], v[204:205], v[120:121], v[122:123] op_sel:[1,0,0] op_sel_hi:[1,1,1]
	v_pk_fma_f32 v[120:121], v[204:205], v[126:127], v[124:125] op_sel:[1,0,0] op_sel_hi:[1,1,1]
	v_pk_fma_f32 v[100:101], v[204:205], v[100:101], v[104:105] op_sel:[1,0,0] op_sel_hi:[1,1,1]
	v_cvt_pk_f32_fp8_e32 v[104:105], v102
	v_cvt_pk_f32_fp8_sdwa v[122:123], v102 src0_sel:WORD_1
	v_cvt_pk_f32_fp8_e32 v[124:125], v103
	v_cvt_pk_f32_fp8_sdwa v[102:103], v103 src0_sel:WORD_1
	v_pk_fma_f32 v[104:105], v[204:205], v[104:105], v[108:109] op_sel:[1,0,0] op_sel_hi:[1,1,1]
	v_pk_fma_f32 v[108:109], v[204:205], v[122:123], v[112:113] op_sel:[1,0,0] op_sel_hi:[1,1,1]
	v_pk_fma_f32 v[112:113], v[204:205], v[124:125], v[116:117] op_sel:[1,0,0] op_sel_hi:[1,1,1]
	v_pk_fma_f32 v[102:103], v[204:205], v[102:103], v[106:107] op_sel:[1,0,0] op_sel_hi:[1,1,1]
	s_waitcnt vmcnt(8)
	v_cvt_pk_f32_fp8_e32 v[110:111], v96
	v_cvt_pk_f32_fp8_sdwa v[116:117], v96 src0_sel:WORD_1
	v_cvt_pk_f32_fp8_e32 v[122:123], v97
	v_cvt_pk_f32_fp8_sdwa v[96:97], v97 src0_sel:WORD_1
	v_pk_fma_f32 v[110:111], v[202:203], v[110:111], v[114:115] op_sel_hi:[0,1,1]
	v_pk_fma_f32 v[114:115], v[202:203], v[116:117], v[118:119] op_sel_hi:[0,1,1]
	v_pk_fma_f32 v[116:117], v[202:203], v[122:123], v[120:121] op_sel_hi:[0,1,1]
	v_pk_fma_f32 v[96:97], v[202:203], v[96:97], v[100:101] op_sel_hi:[0,1,1]
	v_cvt_pk_f32_fp8_e32 v[100:101], v98
	v_cvt_pk_f32_fp8_sdwa v[118:119], v98 src0_sel:WORD_1
	v_cvt_pk_f32_fp8_e32 v[120:121], v99
	v_cvt_pk_f32_fp8_sdwa v[98:99], v99 src0_sel:WORD_1
	v_pk_fma_f32 v[100:101], v[202:203], v[100:101], v[104:105] op_sel_hi:[0,1,1]
	v_pk_fma_f32 v[104:105], v[202:203], v[118:119], v[108:109] op_sel_hi:[0,1,1]
	v_pk_fma_f32 v[108:109], v[202:203], v[120:121], v[112:113] op_sel_hi:[0,1,1]
	v_pk_fma_f32 v[98:99], v[202:203], v[98:99], v[102:103] op_sel_hi:[0,1,1]
	s_waitcnt vmcnt(7)
	v_cvt_pk_f32_fp8_e32 v[106:107], v92
	v_cvt_pk_f32_fp8_sdwa v[112:113], v92 src0_sel:WORD_1
	v_cvt_pk_f32_fp8_e32 v[118:119], v93
	v_cvt_pk_f32_fp8_sdwa v[92:93], v93 src0_sel:WORD_1
	v_pk_fma_f32 v[106:107], v[202:203], v[106:107], v[110:111] op_sel:[1,0,0] op_sel_hi:[1,1,1]
	v_pk_fma_f32 v[110:111], v[202:203], v[112:113], v[114:115] op_sel:[1,0,0] op_sel_hi:[1,1,1]
	v_pk_fma_f32 v[112:113], v[202:203], v[118:119], v[116:117] op_sel:[1,0,0] op_sel_hi:[1,1,1]
	v_pk_fma_f32 v[92:93], v[202:203], v[92:93], v[96:97] op_sel:[1,0,0] op_sel_hi:[1,1,1]
	v_cvt_pk_f32_fp8_e32 v[96:97], v94
	v_cvt_pk_f32_fp8_sdwa v[114:115], v94 src0_sel:WORD_1
	v_cvt_pk_f32_fp8_e32 v[116:117], v95
	v_cvt_pk_f32_fp8_sdwa v[94:95], v95 src0_sel:WORD_1
	v_pk_fma_f32 v[96:97], v[202:203], v[96:97], v[100:101] op_sel:[1,0,0] op_sel_hi:[1,1,1]
	v_pk_fma_f32 v[100:101], v[202:203], v[114:115], v[104:105] op_sel:[1,0,0] op_sel_hi:[1,1,1]
	v_pk_fma_f32 v[104:105], v[202:203], v[116:117], v[108:109] op_sel:[1,0,0] op_sel_hi:[1,1,1]
	v_pk_fma_f32 v[94:95], v[202:203], v[94:95], v[98:99] op_sel:[1,0,0] op_sel_hi:[1,1,1]
	s_waitcnt vmcnt(6)
; DI void up_math(const u32x4 (&W)[16], const u32 (&pj)[16], float* __restrict__ yrow, int lane) {
;   f2 y[8];
; #pragma unroll
;   for (int i = 0; i < 8; ++i) y[i] = f2{0.f, 0.f};
; #pragma unroll
;   for (int j = 0; j < 16; ++j) {
;     const float h = __uint_as_float(pj[j] << 16);
;     const f2 hh = {h, h};
; #pragma unroll
;     for (int d = 0; d < 4; ++d) {
;       f2 lo = __builtin_amdgcn_cvt_pk_f32_fp8((int)W[j][d], false);
;       f2 hi = __builtin_amdgcn_cvt_pk_f32_fp8((int)W[j][d], true);
;       y[2 * d] = lo * hh + y[2 * d];
;       y[2 * d + 1] = hi * hh + y[2 * d + 1];
;     }
;   }
	v_cvt_pk_f32_fp8_e32 v[102:103], v88
	v_cvt_pk_f32_fp8_sdwa v[108:109], v88 src0_sel:WORD_1
	v_cvt_pk_f32_fp8_e32 v[114:115], v89
	v_cvt_pk_f32_fp8_sdwa v[88:89], v89 src0_sel:WORD_1
	v_pk_fma_f32 v[102:103], v[200:201], v[102:103], v[106:107] op_sel_hi:[0,1,1]
	v_pk_fma_f32 v[106:107], v[200:201], v[108:109], v[110:111] op_sel_hi:[0,1,1]
	v_pk_fma_f32 v[108:109], v[200:201], v[114:115], v[112:113] op_sel_hi:[0,1,1]
	v_pk_fma_f32 v[88:89], v[200:201], v[88:89], v[92:93] op_sel_hi:[0,1,1]
	v_cvt_pk_f32_fp8_e32 v[92:93], v90
	v_cvt_pk_f32_fp8_sdwa v[110:111], v90 src0_sel:WORD_1
	v_cvt_pk_f32_fp8_e32 v[112:113], v91
	v_cvt_pk_f32_fp8_sdwa v[90:91], v91 src0_sel:WORD_1
	v_pk_fma_f32 v[92:93], v[200:201], v[92:93], v[96:97] op_sel_hi:[0,1,1]
	v_pk_fma_f32 v[96:97], v[200:201], v[110:111], v[100:101] op_sel_hi:[0,1,1]
	v_pk_fma_f32 v[100:101], v[200:201], v[112:113], v[104:105] op_sel_hi:[0,1,1]
	v_pk_fma_f32 v[90:91], v[200:201], v[90:91], v[94:95] op_sel_hi:[0,1,1]
	s_waitcnt vmcnt(5)
	v_cvt_pk_f32_fp8_e32 v[98:99], v84
	v_cvt_pk_f32_fp8_sdwa v[104:105], v84 src0_sel:WORD_1
	v_cvt_pk_f32_fp8_e32 v[110:111], v85
	v_cvt_pk_f32_fp8_sdwa v[84:85], v85 src0_sel:WORD_1
	v_pk_fma_f32 v[98:99], v[200:201], v[98:99], v[102:103] op_sel:[1,0,0] op_sel_hi:[1,1,1]
	v_pk_fma_f32 v[102:103], v[200:201], v[104:105], v[106:107] op_sel:[1,0,0] op_sel_hi:[1,1,1]
	v_pk_fma_f32 v[104:105], v[200:201], v[110:111], v[108:109] op_sel:[1,0,0] op_sel_hi:[1,1,1]
	v_pk_fma_f32 v[84:85], v[200:201], v[84:85], v[88:89] op_sel:[1,0,0] op_sel_hi:[1,1,1]
	v_cvt_pk_f32_fp8_e32 v[88:89], v86
	v_cvt_pk_f32_fp8_sdwa v[106:107], v86 src0_sel:WORD_1
	v_cvt_pk_f32_fp8_e32 v[108:109], v87
	v_cvt_pk_f32_fp8_sdwa v[86:87], v87 src0_sel:WORD_1
	v_pk_fma_f32 v[88:89], v[200:201], v[88:89], v[92:93] op_sel:[1,0,0] op_sel_hi:[1,1,1]
	v_pk_fma_f32 v[92:93], v[200:201], v[106:107], v[96:97] op_sel:[1,0,0] op_sel_hi:[1,1,1]
	v_pk_fma_f32 v[96:97], v[200:201], v[108:109], v[100:101] op_sel:[1,0,0] op_sel_hi:[1,1,1]
	v_pk_fma_f32 v[86:87], v[200:201], v[86:87], v[90:91] op_sel:[1,0,0] op_sel_hi:[1,1,1]
	s_waitcnt vmcnt(4)
	v_cvt_pk_f32_fp8_e32 v[94:95], v80
	v_cvt_pk_f32_fp8_sdwa v[100:101], v80 src0_sel:WORD_1
	v_cvt_pk_f32_fp8_e32 v[106:107], v81
	v_cvt_pk_f32_fp8_sdwa v[80:81], v81 src0_sel:WORD_1
	v_pk_fma_f32 v[94:95], v[198:199], v[94:95], v[98:99] op_sel_hi:[0,1,1]
	v_pk_fma_f32 v[98:99], v[198:199], v[100:101], v[102:103] op_sel_hi:[0,1,1]
	v_pk_fma_f32 v[100:101], v[198:199], v[106:107], v[104:105] op_sel_hi:[0,1,1]
	v_pk_fma_f32 v[80:81], v[198:199], v[80:81], v[84:85] op_sel_hi:[0,1,1]
	v_cvt_pk_f32_fp8_e32 v[84:85], v82
	v_cvt_pk_f32_fp8_sdwa v[102:103], v82 src0_sel:WORD_1
	v_cvt_pk_f32_fp8_e32 v[104:105], v83
	v_cvt_pk_f32_fp8_sdwa v[82:83], v83 src0_sel:WORD_1
	v_pk_fma_f32 v[84:85], v[198:199], v[84:85], v[88:89] op_sel_hi:[0,1,1]
	v_pk_fma_f32 v[88:89], v[198:199], v[102:103], v[92:93] op_sel_hi:[0,1,1]
	v_pk_fma_f32 v[92:93], v[198:199], v[104:105], v[96:97] op_sel_hi:[0,1,1]
	v_pk_fma_f32 v[82:83], v[198:199], v[82:83], v[86:87] op_sel_hi:[0,1,1]
	s_waitcnt vmcnt(3)
	v_cvt_pk_f32_fp8_e32 v[90:91], v76
	v_cvt_pk_f32_fp8_sdwa v[96:97], v76 src0_sel:WORD_1
	v_cvt_pk_f32_fp8_e32 v[102:103], v77
	v_cvt_pk_f32_fp8_sdwa v[76:77], v77 src0_sel:WORD_1
	v_pk_fma_f32 v[90:91], v[198:199], v[90:91], v[94:95] op_sel:[1,0,0] op_sel_hi:[1,1,1]
	v_pk_fma_f32 v[94:95], v[198:199], v[96:97], v[98:99] op_sel:[1,0,0] op_sel_hi:[1,1,1]
	v_pk_fma_f32 v[96:97], v[198:199], v[102:103], v[100:101] op_sel:[1,0,0] op_sel_hi:[1,1,1]
	v_pk_fma_f32 v[76:77], v[198:199], v[76:77], v[80:81] op_sel:[1,0,0] op_sel_hi:[1,1,1]
	v_cvt_pk_f32_fp8_e32 v[80:81], v78
	v_cvt_pk_f32_fp8_sdwa v[98:99], v78 src0_sel:WORD_1
	v_cvt_pk_f32_fp8_e32 v[100:101], v79
	v_cvt_pk_f32_fp8_sdwa v[78:79], v79 src0_sel:WORD_1
	v_pk_fma_f32 v[80:81], v[198:199], v[80:81], v[84:85] op_sel:[1,0,0] op_sel_hi:[1,1,1]
	v_pk_fma_f32 v[84:85], v[198:199], v[98:99], v[88:89] op_sel:[1,0,0] op_sel_hi:[1,1,1]
	v_pk_fma_f32 v[88:89], v[198:199], v[100:101], v[92:93] op_sel:[1,0,0] op_sel_hi:[1,1,1]
	v_pk_fma_f32 v[78:79], v[198:199], v[78:79], v[82:83] op_sel:[1,0,0] op_sel_hi:[1,1,1]
	s_waitcnt vmcnt(2)
	v_cvt_pk_f32_fp8_e32 v[86:87], v72
	v_cvt_pk_f32_fp8_sdwa v[92:93], v72 src0_sel:WORD_1
	v_cvt_pk_f32_fp8_e32 v[98:99], v73
	v_cvt_pk_f32_fp8_sdwa v[72:73], v73 src0_sel:WORD_1
	v_pk_fma_f32 v[86:87], v[196:197], v[86:87], v[90:91] op_sel_hi:[0,1,1]
	v_pk_fma_f32 v[90:91], v[196:197], v[92:93], v[94:95] op_sel_hi:[0,1,1]
	v_pk_fma_f32 v[92:93], v[196:197], v[98:99], v[96:97] op_sel_hi:[0,1,1]
	v_pk_fma_f32 v[72:73], v[196:197], v[72:73], v[76:77] op_sel_hi:[0,1,1]
	v_cvt_pk_f32_fp8_e32 v[76:77], v74
	v_cvt_pk_f32_fp8_sdwa v[94:95], v74 src0_sel:WORD_1
	v_cvt_pk_f32_fp8_e32 v[96:97], v75
	v_cvt_pk_f32_fp8_sdwa v[74:75], v75 src0_sel:WORD_1
	v_pk_fma_f32 v[76:77], v[196:197], v[76:77], v[80:81] op_sel_hi:[0,1,1]
	v_pk_fma_f32 v[80:81], v[196:197], v[94:95], v[84:85] op_sel_hi:[0,1,1]
	v_pk_fma_f32 v[84:85], v[196:197], v[96:97], v[88:89] op_sel_hi:[0,1,1]
	v_pk_fma_f32 v[74:75], v[196:197], v[74:75], v[78:79] op_sel_hi:[0,1,1]
	s_waitcnt vmcnt(1)
; DI void up_issue(u32x4 (&W)[16], u32 (&pj)[16], const u32* pl, const unsigned char* wbase, int grp) {
; #pragma unroll
;   for (int j = 0; j < 16; ++j) {
;     pj[j] = pl[8 * j + grp];
;     W[j] = *(const u32x4*)(wbase + (size_t)(pj[j] >> 16) * 1024);
;   }
; DI void up_math(const u32x4 (&W)[16], const u32 (&pj)[16], float* __restrict__ yrow, int lane) {
;     ...
;   for (int j = 0; j < 16; ++j) {
;     const float h = __uint_as_float(pj[j] << 16);
;     const f2 hh = {h, h};
; #pragma unroll
;     for (int d = 0; d < 4; ++d) {
;       f2 lo = __builtin_amdgcn_cvt_pk_f32_fp8((int)W[j][d], false);
;       f2 hi = __builtin_amdgcn_cvt_pk_f32_fp8((int)W[j][d], true);
;       y[2 * d] = lo * hh + y[2 * d];
;       y[2 * d + 1] = hi * hh + y[2 * d + 1];
;     }
;   }
;   const bool b5 = lane & 32, b4 = lane & 16, b3 = lane & 8;
;   f2 q4[4];
; #pragma unroll
;   for (int i = 0; i < 4; ++i) {
;     f2 snd = b5 ? y[i] : y[i + 4]; f2 kp = b5 ? y[i + 4] : y[i];
;     q4[i] = f2{kp.x + __shfl_xor(snd.x, 32), kp.y + __shfl_xor(snd.y, 32)};
;   }
;   f2 r2[2];
; #pragma unroll
;   for (int i = 0; i < 2; ++i) {
;     f2 snd = b4 ? q4[i] : q4[i + 2]; f2 kp = b4 ? q4[i + 2] : q4[i];
;     r2[i] = f2{kp.x + __shfl_xor(snd.x, 16), kp.y + __shfl_xor(snd.y, 16)};
;   }
;   f2 a;
;   { f2 snd = b3 ? r2[0] : r2[1]; f2 kp = b3 ? r2[1] : r2[0]; a = f2{kp.x + __shfl_xor(snd.x, 8), kp.y + __shfl_xor(snd.y, 8)}; }
;   const int ci = (b5 ? 4 : 0) + (b4 ? 2 : 0) + (b3 ? 1 : 0);
;   *(float2*)(yrow + (lane & 7) * 16 + 2 * ci) = make_float2(a.x, a.y);
	v_cvt_pk_f32_fp8_e32 v[82:83], v68
	v_cvt_pk_f32_fp8_sdwa v[88:89], v68 src0_sel:WORD_1
	v_cvt_pk_f32_fp8_e32 v[94:95], v69
	v_cvt_pk_f32_fp8_sdwa v[68:69], v69 src0_sel:WORD_1
	v_pk_fma_f32 v[82:83], v[196:197], v[82:83], v[86:87] op_sel:[1,0,0] op_sel_hi:[1,1,1]
	v_pk_fma_f32 v[86:87], v[196:197], v[88:89], v[90:91] op_sel:[1,0,0] op_sel_hi:[1,1,1]
	v_pk_fma_f32 v[68:69], v[196:197], v[68:69], v[72:73] op_sel:[1,0,0] op_sel_hi:[1,1,1]
	v_cvt_pk_f32_fp8_e32 v[72:73], v70
	v_pk_fma_f32 v[88:89], v[196:197], v[94:95], v[92:93] op_sel:[1,0,0] op_sel_hi:[1,1,1]
	v_cvt_pk_f32_fp8_sdwa v[90:91], v70 src0_sel:WORD_1
	v_cvt_pk_f32_fp8_e32 v[92:93], v71
	v_cvt_pk_f32_fp8_sdwa v[70:71], v71 src0_sel:WORD_1
	v_pk_fma_f32 v[72:73], v[196:197], v[72:73], v[76:77] op_sel:[1,0,0] op_sel_hi:[1,1,1]
	v_pk_fma_f32 v[76:77], v[196:197], v[90:91], v[80:81] op_sel:[1,0,0] op_sel_hi:[1,1,1]
	v_pk_fma_f32 v[80:81], v[196:197], v[92:93], v[84:85] op_sel:[1,0,0] op_sel_hi:[1,1,1]
	v_pk_fma_f32 v[70:71], v[196:197], v[70:71], v[74:75] op_sel:[1,0,0] op_sel_hi:[1,1,1]
	s_nop 1
	v_permlane32_swap_b32_e32 v82, v72
	v_permlane32_swap_b32_e32 v83, v73
	v_permlane32_swap_b32_e32 v86, v76
	v_permlane32_swap_b32_e32 v87, v77
	v_permlane32_swap_b32_e32 v88, v80
	v_permlane32_swap_b32_e32 v89, v81
	v_permlane32_swap_b32_e32 v68, v70
	v_permlane32_swap_b32_e32 v69, v71
	v_pk_add_f32 v[72:73], v[82:83], v[72:73]
	v_pk_add_f32 v[74:75], v[86:87], v[76:77]
	v_pk_add_f32 v[76:77], v[88:89], v[80:81]
	v_pk_add_f32 v[68:69], v[68:69], v[70:71]
	s_nop 1
	v_permlane16_swap_b32_e32 v72, v76
	v_permlane16_swap_b32_e32 v73, v77
	v_permlane16_swap_b32_e32 v74, v68
	v_permlane16_swap_b32_e32 v75, v69
	v_pk_add_f32 v[70:71], v[72:73], v[76:77]
	v_pk_add_f32 v[68:69], v[74:75], v[68:69]
	s_nop 1
	v_add_f32_dpp v68, v68, v68 row_shr:8 row_mask:0xf bank_mask:0xc
	v_add_f32_dpp v69, v69, v69 row_shr:8 row_mask:0xf bank_mask:0xc
	v_add_f32_dpp v68, v70, v70 row_shl:8 row_mask:0xf bank_mask:0x3
	v_add_f32_dpp v69, v71, v71 row_shl:8 row_mask:0xf bank_mask:0x3
	v_add_co_u32_e32 v70, vcc, 0x1000, v188
	v_addc_co_u32_e32 v71, vcc, 0, v189, vcc
	global_store_dwordx2 v[70:71], v[68:69], off
	v_add_u32_e32 v145, 0x400, v145
	v_lshl_add_u64 v[188:189], v[188:189], 0, s[18:19]
	s_and_b64 vcc, exec, s[28:29]
	s_cbranch_vccnz .LBB0_1637
.LBB0_1650:
	v_mov_b32_e32 v210, 0
	v_mov_b32_e32 v211, 0
	v_mov_b32_e32 v208, 0
	v_mov_b32_e32 v209, 0
	v_mov_b32_e32 v206, 0
	v_mov_b32_e32 v207, 0
	ds_read_u16_d16_hi v210, v145
	ds_read_u16_d16_hi v211, v145 offset:32
	ds_read_u16_d16_hi v208, v145 offset:64
	ds_read_u16_d16_hi v209, v145 offset:96
	ds_read_u16_d16_hi v206, v145 offset:128
	ds_read_u16_d16_hi v207, v145 offset:160
	ds_read_u16_d16_hi v204, v145 offset:192
	ds_read_u16_d16_hi v205, v145 offset:224
	ds_read_u16_d16_hi v202, v145 offset:256
	ds_read_u16_d16_hi v203, v145 offset:288
	ds_read_u16_d16_hi v200, v145 offset:320
	ds_read_u16_d16_hi v201, v145 offset:352
	ds_read_u16_d16_hi v198, v145 offset:384
	ds_read_u16_d16_hi v199, v145 offset:416
	ds_read_u16_d16_hi v196, v145 offset:448
	ds_read_u16_d16_hi v197, v145 offset:480
	ds_read_u16 v128, v145 offset:2
	ds_read_u16 v124, v145 offset:34
	ds_read_u16 v120, v145 offset:66
	ds_read_u16 v116, v145 offset:98
	ds_read_u16 v112, v145 offset:130
	ds_read_u16 v108, v145 offset:162
	ds_read_u16 v104, v145 offset:194
	ds_read_u16 v100, v145 offset:226
	ds_read_u16 v96, v145 offset:258
	ds_read_u16 v92, v145 offset:290
	ds_read_u16 v88, v145 offset:322
	ds_read_u16 v84, v145 offset:354
	ds_read_u16 v80, v145 offset:386
	ds_read_u16 v76, v145 offset:418
	ds_read_u16 v72, v145 offset:450
	ds_read_u16 v68, v145 offset:482
	s_waitcnt lgkmcnt(15)
	v_lshl_add_u32 v128, v128, 10, v250
	global_load_dwordx4 v[128:131], v128, s[98:99]
	s_waitcnt lgkmcnt(14)
	v_lshl_add_u32 v124, v124, 10, v250
	global_load_dwordx4 v[124:127], v124, s[98:99]
	s_waitcnt lgkmcnt(13)
	v_lshl_add_u32 v120, v120, 10, v250
	global_load_dwordx4 v[120:123], v120, s[98:99]
	s_waitcnt lgkmcnt(12)
	v_lshl_add_u32 v116, v116, 10, v250
	global_load_dwordx4 v[116:119], v116, s[98:99]
	s_waitcnt lgkmcnt(11)
	v_lshl_add_u32 v112, v112, 10, v250
	global_load_dwordx4 v[112:115], v112, s[98:99]
	s_waitcnt lgkmcnt(10)
	v_lshl_add_u32 v108, v108, 10, v250
	global_load_dwordx4 v[108:111], v108, s[98:99]
	s_waitcnt lgkmcnt(9)
	v_lshl_add_u32 v104, v104, 10, v250
	global_load_dwordx4 v[104:107], v104, s[98:99]
	s_waitcnt lgkmcnt(8)
	v_lshl_add_u32 v100, v100, 10, v250
	global_load_dwordx4 v[100:103], v100, s[98:99]
	s_waitcnt lgkmcnt(7)
	v_lshl_add_u32 v96, v96, 10, v250
	global_load_dwordx4 v[96:99], v96, s[98:99]
	s_waitcnt lgkmcnt(6)
	v_lshl_add_u32 v92, v92, 10, v250
	global_load_dwordx4 v[92:95], v92, s[98:99]
	s_waitcnt lgkmcnt(5)
	v_lshl_add_u32 v88, v88, 10, v250
	global_load_dwordx4 v[88:91], v88, s[98:99]
	s_waitcnt lgkmcnt(4)
	v_lshl_add_u32 v84, v84, 10, v250
	global_load_dwordx4 v[84:87], v84, s[98:99]
	s_waitcnt lgkmcnt(3)
	v_lshl_add_u32 v80, v80, 10, v250
	global_load_dwordx4 v[80:83], v80, s[98:99]
	s_waitcnt lgkmcnt(2)
	v_lshl_add_u32 v76, v76, 10, v250
	global_load_dwordx4 v[76:79], v76, s[98:99]
	s_waitcnt lgkmcnt(1)
	v_lshl_add_u32 v72, v72, 10, v250
	global_load_dwordx4 v[72:75], v72, s[98:99]
	s_waitcnt lgkmcnt(0)
	v_lshl_add_u32 v68, v68, 10, v250
	global_load_dwordx4 v[68:71], v68, s[98:99]
	s_waitcnt vmcnt(31)
	v_cvt_pk_f32_fp8_e32 v[216:217], v4
	v_cvt_pk_f32_fp8_sdwa v[226:227], v4 src0_sel:WORD_1
	v_cvt_pk_f32_fp8_e32 v[228:229], v5
	v_cvt_pk_f32_fp8_sdwa v[230:231], v5 src0_sel:WORD_1
	v_cvt_pk_f32_fp8_e32 v[232:233], v6
	v_cvt_pk_f32_fp8_sdwa v[234:235], v6 src0_sel:WORD_1
	v_cvt_pk_f32_fp8_e32 v[236:237], v7
	v_cvt_pk_f32_fp8_sdwa v[238:239], v7 src0_sel:WORD_1
	s_waitcnt vmcnt(30)
; DI void up_math(const u32x4 (&W)[16], const u32 (&pj)[16], float* __restrict__ yrow, int lane) {
;   f2 y[8];
; #pragma unroll
;   for (int i = 0; i < 8; ++i) y[i] = f2{0.f, 0.f};
; #pragma unroll
;   for (int j = 0; j < 16; ++j) {
;     const float h = __uint_as_float(pj[j] << 16);
;     const f2 hh = {h, h};
; #pragma unroll
;     for (int d = 0; d < 4; ++d) {
;       f2 lo = __builtin_amdgcn_cvt_pk_f32_fp8((int)W[j][d], false);
;       f2 hi = __builtin_amdgcn_cvt_pk_f32_fp8((int)W[j][d], true);
;       y[2 * d] = lo * hh + y[2 * d];
;       y[2 * d + 1] = hi * hh + y[2 * d + 1];
;     }
;   }
	v_cvt_pk_f32_fp8_e32 v[240:241], v8
	v_cvt_pk_f32_fp8_sdwa v[242:243], v8 src0_sel:WORD_1
	v_cvt_pk_f32_fp8_e32 v[244:245], v9
	v_cvt_pk_f32_fp8_sdwa v[246:247], v9 src0_sel:WORD_1
	v_pk_fma_f32 v[216:217], v[178:179], v[216:217], 0 op_sel_hi:[0,1,0]
	v_pk_fma_f32 v[226:227], v[178:179], v[226:227], 0 op_sel_hi:[0,1,0]
	v_pk_fma_f32 v[228:229], v[178:179], v[228:229], 0 op_sel_hi:[0,1,0]
	v_pk_fma_f32 v[230:231], v[178:179], v[230:231], 0 op_sel_hi:[0,1,0]
	v_pk_fma_f32 v[232:233], v[178:179], v[232:233], 0 op_sel_hi:[0,1,0]
	v_pk_fma_f32 v[234:235], v[178:179], v[234:235], 0 op_sel_hi:[0,1,0]
	v_pk_fma_f32 v[236:237], v[178:179], v[236:237], 0 op_sel_hi:[0,1,0]
	v_pk_fma_f32 v[238:239], v[178:179], v[238:239], 0 op_sel_hi:[0,1,0]
	v_pk_fma_f32 v[216:217], v[178:179], v[240:241], v[216:217] op_sel:[1,0,0] op_sel_hi:[1,1,1]
	v_cvt_pk_f32_fp8_e32 v[240:241], v10
	v_pk_fma_f32 v[226:227], v[178:179], v[242:243], v[226:227] op_sel:[1,0,0] op_sel_hi:[1,1,1]
	v_pk_fma_f32 v[228:229], v[178:179], v[244:245], v[228:229] op_sel:[1,0,0] op_sel_hi:[1,1,1]
	v_pk_fma_f32 v[230:231], v[178:179], v[246:247], v[230:231] op_sel:[1,0,0] op_sel_hi:[1,1,1]
	v_cvt_pk_f32_fp8_sdwa v[242:243], v10 src0_sel:WORD_1
	v_cvt_pk_f32_fp8_e32 v[244:245], v11
	v_cvt_pk_f32_fp8_sdwa v[246:247], v11 src0_sel:WORD_1
	v_pk_fma_f32 v[232:233], v[178:179], v[240:241], v[232:233] op_sel:[1,0,0] op_sel_hi:[1,1,1]
	s_waitcnt vmcnt(29)
	v_cvt_pk_f32_fp8_e32 v[240:241], v12
	v_pk_fma_f32 v[234:235], v[178:179], v[242:243], v[234:235] op_sel:[1,0,0] op_sel_hi:[1,1,1]
	v_pk_fma_f32 v[236:237], v[178:179], v[244:245], v[236:237] op_sel:[1,0,0] op_sel_hi:[1,1,1]
	v_pk_fma_f32 v[238:239], v[178:179], v[246:247], v[238:239] op_sel:[1,0,0] op_sel_hi:[1,1,1]
	v_cvt_pk_f32_fp8_sdwa v[242:243], v12 src0_sel:WORD_1
	v_cvt_pk_f32_fp8_e32 v[244:245], v13
	v_cvt_pk_f32_fp8_sdwa v[246:247], v13 src0_sel:WORD_1
	v_pk_fma_f32 v[216:217], v[180:181], v[240:241], v[216:217] op_sel_hi:[0,1,1]
	v_cvt_pk_f32_fp8_e32 v[240:241], v14
	v_pk_fma_f32 v[226:227], v[180:181], v[242:243], v[226:227] op_sel_hi:[0,1,1]
	v_pk_fma_f32 v[228:229], v[180:181], v[244:245], v[228:229] op_sel_hi:[0,1,1]
	v_pk_fma_f32 v[230:231], v[180:181], v[246:247], v[230:231] op_sel_hi:[0,1,1]
	v_cvt_pk_f32_fp8_sdwa v[242:243], v14 src0_sel:WORD_1
	v_cvt_pk_f32_fp8_e32 v[244:245], v15
	v_cvt_pk_f32_fp8_sdwa v[246:247], v15 src0_sel:WORD_1
	v_pk_fma_f32 v[232:233], v[180:181], v[240:241], v[232:233] op_sel_hi:[0,1,1]
	s_waitcnt vmcnt(28)
	v_cvt_pk_f32_fp8_e32 v[240:241], v16
	v_pk_fma_f32 v[234:235], v[180:181], v[242:243], v[234:235] op_sel_hi:[0,1,1]
	v_pk_fma_f32 v[236:237], v[180:181], v[244:245], v[236:237] op_sel_hi:[0,1,1]
	v_pk_fma_f32 v[238:239], v[180:181], v[246:247], v[238:239] op_sel_hi:[0,1,1]
	v_cvt_pk_f32_fp8_sdwa v[242:243], v16 src0_sel:WORD_1
	v_cvt_pk_f32_fp8_e32 v[244:245], v17
	v_cvt_pk_f32_fp8_sdwa v[246:247], v17 src0_sel:WORD_1
	v_pk_fma_f32 v[216:217], v[180:181], v[240:241], v[216:217] op_sel:[1,0,0] op_sel_hi:[1,1,1]
	v_cvt_pk_f32_fp8_e32 v[240:241], v18
	v_pk_fma_f32 v[226:227], v[180:181], v[242:243], v[226:227] op_sel:[1,0,0] op_sel_hi:[1,1,1]
	v_pk_fma_f32 v[228:229], v[180:181], v[244:245], v[228:229] op_sel:[1,0,0] op_sel_hi:[1,1,1]
	v_pk_fma_f32 v[230:231], v[180:181], v[246:247], v[230:231] op_sel:[1,0,0] op_sel_hi:[1,1,1]
	v_cvt_pk_f32_fp8_sdwa v[242:243], v18 src0_sel:WORD_1
	v_cvt_pk_f32_fp8_e32 v[244:245], v19
	v_cvt_pk_f32_fp8_sdwa v[246:247], v19 src0_sel:WORD_1
	v_pk_fma_f32 v[232:233], v[180:181], v[240:241], v[232:233] op_sel:[1,0,0] op_sel_hi:[1,1,1]
	s_waitcnt vmcnt(27)
	v_cvt_pk_f32_fp8_e32 v[240:241], v20
	v_pk_fma_f32 v[234:235], v[180:181], v[242:243], v[234:235] op_sel:[1,0,0] op_sel_hi:[1,1,1]
	v_pk_fma_f32 v[236:237], v[180:181], v[244:245], v[236:237] op_sel:[1,0,0] op_sel_hi:[1,1,1]
	v_pk_fma_f32 v[238:239], v[180:181], v[246:247], v[238:239] op_sel:[1,0,0] op_sel_hi:[1,1,1]
	v_cvt_pk_f32_fp8_sdwa v[242:243], v20 src0_sel:WORD_1
	v_cvt_pk_f32_fp8_e32 v[244:245], v21
	v_cvt_pk_f32_fp8_sdwa v[246:247], v21 src0_sel:WORD_1
	v_pk_fma_f32 v[216:217], v[182:183], v[240:241], v[216:217] op_sel_hi:[0,1,1]
	v_cvt_pk_f32_fp8_e32 v[240:241], v22
	v_pk_fma_f32 v[226:227], v[182:183], v[242:243], v[226:227] op_sel_hi:[0,1,1]
	v_pk_fma_f32 v[228:229], v[182:183], v[244:245], v[228:229] op_sel_hi:[0,1,1]
	v_pk_fma_f32 v[230:231], v[182:183], v[246:247], v[230:231] op_sel_hi:[0,1,1]
	v_cvt_pk_f32_fp8_sdwa v[242:243], v22 src0_sel:WORD_1
	v_cvt_pk_f32_fp8_e32 v[244:245], v23
	v_cvt_pk_f32_fp8_sdwa v[246:247], v23 src0_sel:WORD_1
	v_pk_fma_f32 v[232:233], v[182:183], v[240:241], v[232:233] op_sel_hi:[0,1,1]
	s_waitcnt vmcnt(26)
	v_cvt_pk_f32_fp8_e32 v[240:241], v24
	v_pk_fma_f32 v[234:235], v[182:183], v[242:243], v[234:235] op_sel_hi:[0,1,1]
	v_pk_fma_f32 v[236:237], v[182:183], v[244:245], v[236:237] op_sel_hi:[0,1,1]
	v_pk_fma_f32 v[238:239], v[182:183], v[246:247], v[238:239] op_sel_hi:[0,1,1]
	v_cvt_pk_f32_fp8_sdwa v[242:243], v24 src0_sel:WORD_1
	v_cvt_pk_f32_fp8_e32 v[244:245], v25
	v_cvt_pk_f32_fp8_sdwa v[246:247], v25 src0_sel:WORD_1
	v_pk_fma_f32 v[216:217], v[182:183], v[240:241], v[216:217] op_sel:[1,0,0] op_sel_hi:[1,1,1]
	v_cvt_pk_f32_fp8_e32 v[240:241], v26
	v_pk_fma_f32 v[226:227], v[182:183], v[242:243], v[226:227] op_sel:[1,0,0] op_sel_hi:[1,1,1]
	v_pk_fma_f32 v[228:229], v[182:183], v[244:245], v[228:229] op_sel:[1,0,0] op_sel_hi:[1,1,1]
	v_pk_fma_f32 v[230:231], v[182:183], v[246:247], v[230:231] op_sel:[1,0,0] op_sel_hi:[1,1,1]
	v_cvt_pk_f32_fp8_sdwa v[242:243], v26 src0_sel:WORD_1
	v_cvt_pk_f32_fp8_e32 v[244:245], v27
	v_cvt_pk_f32_fp8_sdwa v[246:247], v27 src0_sel:WORD_1
	v_pk_fma_f32 v[232:233], v[182:183], v[240:241], v[232:233] op_sel:[1,0,0] op_sel_hi:[1,1,1]
	s_waitcnt vmcnt(25)
; DI void up_math(const u32x4 (&W)[16], const u32 (&pj)[16], float* __restrict__ yrow, int lane) {
;   f2 y[8];
; #pragma unroll
;   for (int i = 0; i < 8; ++i) y[i] = f2{0.f, 0.f};
; #pragma unroll
;   for (int j = 0; j < 16; ++j) {
;     const float h = __uint_as_float(pj[j] << 16);
;     const f2 hh = {h, h};
; #pragma unroll
;     for (int d = 0; d < 4; ++d) {
;       f2 lo = __builtin_amdgcn_cvt_pk_f32_fp8((int)W[j][d], false);
;       f2 hi = __builtin_amdgcn_cvt_pk_f32_fp8((int)W[j][d], true);
;       y[2 * d] = lo * hh + y[2 * d];
;       y[2 * d + 1] = hi * hh + y[2 * d + 1];
;     }
;   }
	v_cvt_pk_f32_fp8_e32 v[240:241], v28
	v_pk_fma_f32 v[234:235], v[182:183], v[242:243], v[234:235] op_sel:[1,0,0] op_sel_hi:[1,1,1]
	v_pk_fma_f32 v[236:237], v[182:183], v[244:245], v[236:237] op_sel:[1,0,0] op_sel_hi:[1,1,1]
	v_pk_fma_f32 v[238:239], v[182:183], v[246:247], v[238:239] op_sel:[1,0,0] op_sel_hi:[1,1,1]
	v_cvt_pk_f32_fp8_sdwa v[242:243], v28 src0_sel:WORD_1
	v_cvt_pk_f32_fp8_e32 v[244:245], v29
	v_cvt_pk_f32_fp8_sdwa v[246:247], v29 src0_sel:WORD_1
	v_pk_fma_f32 v[216:217], v[184:185], v[240:241], v[216:217] op_sel_hi:[0,1,1]
	v_cvt_pk_f32_fp8_e32 v[240:241], v30
	v_pk_fma_f32 v[226:227], v[184:185], v[242:243], v[226:227] op_sel_hi:[0,1,1]
	v_pk_fma_f32 v[228:229], v[184:185], v[244:245], v[228:229] op_sel_hi:[0,1,1]
	v_pk_fma_f32 v[230:231], v[184:185], v[246:247], v[230:231] op_sel_hi:[0,1,1]
	v_cvt_pk_f32_fp8_sdwa v[242:243], v30 src0_sel:WORD_1
	v_cvt_pk_f32_fp8_e32 v[244:245], v31
	v_cvt_pk_f32_fp8_sdwa v[246:247], v31 src0_sel:WORD_1
	v_pk_fma_f32 v[232:233], v[184:185], v[240:241], v[232:233] op_sel_hi:[0,1,1]
	s_waitcnt vmcnt(24)
	v_cvt_pk_f32_fp8_e32 v[240:241], v32
	v_pk_fma_f32 v[234:235], v[184:185], v[242:243], v[234:235] op_sel_hi:[0,1,1]
	v_pk_fma_f32 v[236:237], v[184:185], v[244:245], v[236:237] op_sel_hi:[0,1,1]
	v_pk_fma_f32 v[238:239], v[184:185], v[246:247], v[238:239] op_sel_hi:[0,1,1]
	v_cvt_pk_f32_fp8_sdwa v[242:243], v32 src0_sel:WORD_1
	v_cvt_pk_f32_fp8_e32 v[244:245], v33
	v_cvt_pk_f32_fp8_sdwa v[246:247], v33 src0_sel:WORD_1
	v_pk_fma_f32 v[216:217], v[184:185], v[240:241], v[216:217] op_sel:[1,0,0] op_sel_hi:[1,1,1]
	v_cvt_pk_f32_fp8_e32 v[240:241], v34
	v_pk_fma_f32 v[226:227], v[184:185], v[242:243], v[226:227] op_sel:[1,0,0] op_sel_hi:[1,1,1]
	v_pk_fma_f32 v[228:229], v[184:185], v[244:245], v[228:229] op_sel:[1,0,0] op_sel_hi:[1,1,1]
	v_pk_fma_f32 v[230:231], v[184:185], v[246:247], v[230:231] op_sel:[1,0,0] op_sel_hi:[1,1,1]
	v_cvt_pk_f32_fp8_sdwa v[242:243], v34 src0_sel:WORD_1
	v_cvt_pk_f32_fp8_e32 v[244:245], v35
	v_cvt_pk_f32_fp8_sdwa v[246:247], v35 src0_sel:WORD_1
	v_pk_fma_f32 v[232:233], v[184:185], v[240:241], v[232:233] op_sel:[1,0,0] op_sel_hi:[1,1,1]
	s_waitcnt vmcnt(23)
	v_cvt_pk_f32_fp8_e32 v[240:241], v36
	v_pk_fma_f32 v[234:235], v[184:185], v[242:243], v[234:235] op_sel:[1,0,0] op_sel_hi:[1,1,1]
	v_pk_fma_f32 v[236:237], v[184:185], v[244:245], v[236:237] op_sel:[1,0,0] op_sel_hi:[1,1,1]
	v_pk_fma_f32 v[238:239], v[184:185], v[246:247], v[238:239] op_sel:[1,0,0] op_sel_hi:[1,1,1]
	v_cvt_pk_f32_fp8_sdwa v[242:243], v36 src0_sel:WORD_1
	v_cvt_pk_f32_fp8_e32 v[244:245], v37
	v_cvt_pk_f32_fp8_sdwa v[246:247], v37 src0_sel:WORD_1
	v_pk_fma_f32 v[216:217], v[186:187], v[240:241], v[216:217] op_sel_hi:[0,1,1]
	v_cvt_pk_f32_fp8_e32 v[240:241], v38
	v_pk_fma_f32 v[226:227], v[186:187], v[242:243], v[226:227] op_sel_hi:[0,1,1]
	v_pk_fma_f32 v[228:229], v[186:187], v[244:245], v[228:229] op_sel_hi:[0,1,1]
	v_pk_fma_f32 v[230:231], v[186:187], v[246:247], v[230:231] op_sel_hi:[0,1,1]
	v_cvt_pk_f32_fp8_sdwa v[242:243], v38 src0_sel:WORD_1
	v_cvt_pk_f32_fp8_e32 v[244:245], v39
	v_cvt_pk_f32_fp8_sdwa v[246:247], v39 src0_sel:WORD_1
	v_pk_fma_f32 v[232:233], v[186:187], v[240:241], v[232:233] op_sel_hi:[0,1,1]
	s_waitcnt vmcnt(22)
	v_cvt_pk_f32_fp8_e32 v[240:241], v40
	v_pk_fma_f32 v[234:235], v[186:187], v[242:243], v[234:235] op_sel_hi:[0,1,1]
	v_pk_fma_f32 v[236:237], v[186:187], v[244:245], v[236:237] op_sel_hi:[0,1,1]
	v_pk_fma_f32 v[238:239], v[186:187], v[246:247], v[238:239] op_sel_hi:[0,1,1]
	v_cvt_pk_f32_fp8_sdwa v[242:243], v40 src0_sel:WORD_1
	v_cvt_pk_f32_fp8_e32 v[244:245], v41
	v_cvt_pk_f32_fp8_sdwa v[246:247], v41 src0_sel:WORD_1
	v_pk_fma_f32 v[216:217], v[186:187], v[240:241], v[216:217] op_sel:[1,0,0] op_sel_hi:[1,1,1]
	v_cvt_pk_f32_fp8_e32 v[240:241], v42
	v_pk_fma_f32 v[226:227], v[186:187], v[242:243], v[226:227] op_sel:[1,0,0] op_sel_hi:[1,1,1]
	v_pk_fma_f32 v[228:229], v[186:187], v[244:245], v[228:229] op_sel:[1,0,0] op_sel_hi:[1,1,1]
	v_pk_fma_f32 v[230:231], v[186:187], v[246:247], v[230:231] op_sel:[1,0,0] op_sel_hi:[1,1,1]
	v_cvt_pk_f32_fp8_sdwa v[242:243], v42 src0_sel:WORD_1
	v_cvt_pk_f32_fp8_e32 v[244:245], v43
	v_cvt_pk_f32_fp8_sdwa v[246:247], v43 src0_sel:WORD_1
	v_pk_fma_f32 v[232:233], v[186:187], v[240:241], v[232:233] op_sel:[1,0,0] op_sel_hi:[1,1,1]
	s_waitcnt vmcnt(21)
	v_cvt_pk_f32_fp8_e32 v[240:241], v44
	v_pk_fma_f32 v[234:235], v[186:187], v[242:243], v[234:235] op_sel:[1,0,0] op_sel_hi:[1,1,1]
	v_pk_fma_f32 v[236:237], v[186:187], v[244:245], v[236:237] op_sel:[1,0,0] op_sel_hi:[1,1,1]
	v_pk_fma_f32 v[238:239], v[186:187], v[246:247], v[238:239] op_sel:[1,0,0] op_sel_hi:[1,1,1]
	v_cvt_pk_f32_fp8_sdwa v[242:243], v44 src0_sel:WORD_1
	v_cvt_pk_f32_fp8_e32 v[244:245], v45
	v_cvt_pk_f32_fp8_sdwa v[246:247], v45 src0_sel:WORD_1
	v_pk_fma_f32 v[216:217], v[190:191], v[240:241], v[216:217] op_sel_hi:[0,1,1]
	v_cvt_pk_f32_fp8_e32 v[240:241], v46
	v_pk_fma_f32 v[226:227], v[190:191], v[242:243], v[226:227] op_sel_hi:[0,1,1]
	v_pk_fma_f32 v[228:229], v[190:191], v[244:245], v[228:229] op_sel_hi:[0,1,1]
	v_pk_fma_f32 v[230:231], v[190:191], v[246:247], v[230:231] op_sel_hi:[0,1,1]
	v_cvt_pk_f32_fp8_sdwa v[242:243], v46 src0_sel:WORD_1
	v_cvt_pk_f32_fp8_e32 v[244:245], v47
	v_cvt_pk_f32_fp8_sdwa v[246:247], v47 src0_sel:WORD_1
	v_pk_fma_f32 v[232:233], v[190:191], v[240:241], v[232:233] op_sel_hi:[0,1,1]
	s_waitcnt vmcnt(20)
; DI void up_math(const u32x4 (&W)[16], const u32 (&pj)[16], float* __restrict__ yrow, int lane) {
;     ...
;   for (int j = 0; j < 16; ++j) {
;     const float h = __uint_as_float(pj[j] << 16);
;     const f2 hh = {h, h};
; #pragma unroll
;     for (int d = 0; d < 4; ++d) {
;       f2 lo = __builtin_amdgcn_cvt_pk_f32_fp8((int)W[j][d], false);
;       f2 hi = __builtin_amdgcn_cvt_pk_f32_fp8((int)W[j][d], true);
;       y[2 * d] = lo * hh + y[2 * d];
;       y[2 * d + 1] = hi * hh + y[2 * d + 1];
;     }
;   }
;   const bool b5 = lane & 32, b4 = lane & 16, b3 = lane & 8;
;   f2 q4[4];
; #pragma unroll
;   for (int i = 0; i < 4; ++i) {
;     f2 snd = b5 ? y[i] : y[i + 4]; f2 kp = b5 ? y[i + 4] : y[i];
;     q4[i] = f2{kp.x + __shfl_xor(snd.x, 32), kp.y + __shfl_xor(snd.y, 32)};
;   }
;   f2 r2[2];
; #pragma unroll
;   for (int i = 0; i < 2; ++i) {
;     f2 snd = b4 ? q4[i] : q4[i + 2]; f2 kp = b4 ? q4[i + 2] : q4[i];
;     r2[i] = f2{kp.x + __shfl_xor(snd.x, 16), kp.y + __shfl_xor(snd.y, 16)};
;   }
;   f2 a;
;   { f2 snd = b3 ? r2[0] : r2[1]; f2 kp = b3 ? r2[1] : r2[0]; a = f2{kp.x + __shfl_xor(snd.x, 8), kp.y + __shfl_xor(snd.y, 8)}; }
;   const int ci = (b5 ? 4 : 0) + (b4 ? 2 : 0) + (b3 ? 1 : 0);
;   *(float2*)(yrow + (lane & 7) * 16 + 2 * ci) = make_float2(a.x, a.y);
	v_cvt_pk_f32_fp8_e32 v[240:241], v48
	v_pk_fma_f32 v[234:235], v[190:191], v[242:243], v[234:235] op_sel_hi:[0,1,1]
	v_pk_fma_f32 v[236:237], v[190:191], v[244:245], v[236:237] op_sel_hi:[0,1,1]
	v_pk_fma_f32 v[238:239], v[190:191], v[246:247], v[238:239] op_sel_hi:[0,1,1]
	v_cvt_pk_f32_fp8_sdwa v[242:243], v48 src0_sel:WORD_1
	v_cvt_pk_f32_fp8_e32 v[244:245], v49
	v_cvt_pk_f32_fp8_sdwa v[246:247], v49 src0_sel:WORD_1
	v_pk_fma_f32 v[216:217], v[190:191], v[240:241], v[216:217] op_sel:[1,0,0] op_sel_hi:[1,1,1]
	v_cvt_pk_f32_fp8_e32 v[240:241], v50
	v_pk_fma_f32 v[226:227], v[190:191], v[242:243], v[226:227] op_sel:[1,0,0] op_sel_hi:[1,1,1]
	v_pk_fma_f32 v[228:229], v[190:191], v[244:245], v[228:229] op_sel:[1,0,0] op_sel_hi:[1,1,1]
	v_pk_fma_f32 v[230:231], v[190:191], v[246:247], v[230:231] op_sel:[1,0,0] op_sel_hi:[1,1,1]
	v_cvt_pk_f32_fp8_sdwa v[242:243], v50 src0_sel:WORD_1
	v_cvt_pk_f32_fp8_e32 v[244:245], v51
	v_cvt_pk_f32_fp8_sdwa v[246:247], v51 src0_sel:WORD_1
	v_pk_fma_f32 v[232:233], v[190:191], v[240:241], v[232:233] op_sel:[1,0,0] op_sel_hi:[1,1,1]
	s_waitcnt vmcnt(19)
	v_cvt_pk_f32_fp8_e32 v[240:241], v52
	v_pk_fma_f32 v[234:235], v[190:191], v[242:243], v[234:235] op_sel:[1,0,0] op_sel_hi:[1,1,1]
	v_pk_fma_f32 v[236:237], v[190:191], v[244:245], v[236:237] op_sel:[1,0,0] op_sel_hi:[1,1,1]
	v_pk_fma_f32 v[238:239], v[190:191], v[246:247], v[238:239] op_sel:[1,0,0] op_sel_hi:[1,1,1]
	v_cvt_pk_f32_fp8_sdwa v[242:243], v52 src0_sel:WORD_1
	v_cvt_pk_f32_fp8_e32 v[244:245], v53
	v_cvt_pk_f32_fp8_sdwa v[246:247], v53 src0_sel:WORD_1
	v_pk_fma_f32 v[216:217], v[192:193], v[240:241], v[216:217] op_sel_hi:[0,1,1]
	v_cvt_pk_f32_fp8_e32 v[240:241], v54
	v_pk_fma_f32 v[226:227], v[192:193], v[242:243], v[226:227] op_sel_hi:[0,1,1]
	v_pk_fma_f32 v[228:229], v[192:193], v[244:245], v[228:229] op_sel_hi:[0,1,1]
	v_pk_fma_f32 v[230:231], v[192:193], v[246:247], v[230:231] op_sel_hi:[0,1,1]
	v_cvt_pk_f32_fp8_sdwa v[242:243], v54 src0_sel:WORD_1
	v_cvt_pk_f32_fp8_e32 v[244:245], v55
	v_cvt_pk_f32_fp8_sdwa v[246:247], v55 src0_sel:WORD_1
	v_pk_fma_f32 v[232:233], v[192:193], v[240:241], v[232:233] op_sel_hi:[0,1,1]
	s_waitcnt vmcnt(18)
	v_cvt_pk_f32_fp8_e32 v[240:241], v56
	v_pk_fma_f32 v[234:235], v[192:193], v[242:243], v[234:235] op_sel_hi:[0,1,1]
	v_pk_fma_f32 v[236:237], v[192:193], v[244:245], v[236:237] op_sel_hi:[0,1,1]
	v_pk_fma_f32 v[238:239], v[192:193], v[246:247], v[238:239] op_sel_hi:[0,1,1]
	v_cvt_pk_f32_fp8_sdwa v[242:243], v56 src0_sel:WORD_1
	v_cvt_pk_f32_fp8_e32 v[244:245], v57
	v_cvt_pk_f32_fp8_sdwa v[246:247], v57 src0_sel:WORD_1
	v_pk_fma_f32 v[216:217], v[192:193], v[240:241], v[216:217] op_sel:[1,0,0] op_sel_hi:[1,1,1]
	v_cvt_pk_f32_fp8_e32 v[240:241], v58
	v_pk_fma_f32 v[226:227], v[192:193], v[242:243], v[226:227] op_sel:[1,0,0] op_sel_hi:[1,1,1]
	v_pk_fma_f32 v[228:229], v[192:193], v[244:245], v[228:229] op_sel:[1,0,0] op_sel_hi:[1,1,1]
	v_pk_fma_f32 v[230:231], v[192:193], v[246:247], v[230:231] op_sel:[1,0,0] op_sel_hi:[1,1,1]
	v_cvt_pk_f32_fp8_sdwa v[242:243], v58 src0_sel:WORD_1
	v_cvt_pk_f32_fp8_e32 v[244:245], v59
	v_cvt_pk_f32_fp8_sdwa v[246:247], v59 src0_sel:WORD_1
	v_pk_fma_f32 v[232:233], v[192:193], v[240:241], v[232:233] op_sel:[1,0,0] op_sel_hi:[1,1,1]
	s_waitcnt vmcnt(17)
	v_cvt_pk_f32_fp8_e32 v[240:241], v60
	v_pk_fma_f32 v[234:235], v[192:193], v[242:243], v[234:235] op_sel:[1,0,0] op_sel_hi:[1,1,1]
	v_pk_fma_f32 v[236:237], v[192:193], v[244:245], v[236:237] op_sel:[1,0,0] op_sel_hi:[1,1,1]
	v_pk_fma_f32 v[238:239], v[192:193], v[246:247], v[238:239] op_sel:[1,0,0] op_sel_hi:[1,1,1]
	v_cvt_pk_f32_fp8_sdwa v[242:243], v60 src0_sel:WORD_1
	v_cvt_pk_f32_fp8_e32 v[244:245], v61
	v_cvt_pk_f32_fp8_sdwa v[246:247], v61 src0_sel:WORD_1
	v_pk_fma_f32 v[216:217], v[194:195], v[240:241], v[216:217] op_sel_hi:[0,1,1]
	v_cvt_pk_f32_fp8_e32 v[240:241], v62
	v_pk_fma_f32 v[226:227], v[194:195], v[242:243], v[226:227] op_sel_hi:[0,1,1]
	v_pk_fma_f32 v[228:229], v[194:195], v[244:245], v[228:229] op_sel_hi:[0,1,1]
	v_pk_fma_f32 v[230:231], v[194:195], v[246:247], v[230:231] op_sel_hi:[0,1,1]
	v_cvt_pk_f32_fp8_sdwa v[242:243], v62 src0_sel:WORD_1
	v_cvt_pk_f32_fp8_e32 v[244:245], v63
	v_cvt_pk_f32_fp8_sdwa v[246:247], v63 src0_sel:WORD_1
	v_pk_fma_f32 v[232:233], v[194:195], v[240:241], v[232:233] op_sel_hi:[0,1,1]
	s_waitcnt vmcnt(16)
	v_cvt_pk_f32_fp8_e32 v[240:241], v64
	v_pk_fma_f32 v[234:235], v[194:195], v[242:243], v[234:235] op_sel_hi:[0,1,1]
	v_pk_fma_f32 v[236:237], v[194:195], v[244:245], v[236:237] op_sel_hi:[0,1,1]
	v_pk_fma_f32 v[238:239], v[194:195], v[246:247], v[238:239] op_sel_hi:[0,1,1]
	v_cvt_pk_f32_fp8_sdwa v[242:243], v64 src0_sel:WORD_1
	v_cvt_pk_f32_fp8_e32 v[244:245], v65
	v_cvt_pk_f32_fp8_sdwa v[246:247], v65 src0_sel:WORD_1
	v_pk_fma_f32 v[216:217], v[194:195], v[240:241], v[216:217] op_sel:[1,0,0] op_sel_hi:[1,1,1]
	v_cvt_pk_f32_fp8_e32 v[240:241], v66
	v_pk_fma_f32 v[226:227], v[194:195], v[242:243], v[226:227] op_sel:[1,0,0] op_sel_hi:[1,1,1]
	v_pk_fma_f32 v[228:229], v[194:195], v[244:245], v[228:229] op_sel:[1,0,0] op_sel_hi:[1,1,1]
	v_pk_fma_f32 v[230:231], v[194:195], v[246:247], v[230:231] op_sel:[1,0,0] op_sel_hi:[1,1,1]
	v_cvt_pk_f32_fp8_sdwa v[242:243], v66 src0_sel:WORD_1
	v_cvt_pk_f32_fp8_e32 v[244:245], v67
	v_cvt_pk_f32_fp8_sdwa v[246:247], v67 src0_sel:WORD_1
	v_pk_fma_f32 v[232:233], v[194:195], v[240:241], v[232:233] op_sel:[1,0,0] op_sel_hi:[1,1,1]
	v_pk_fma_f32 v[234:235], v[194:195], v[242:243], v[234:235] op_sel:[1,0,0] op_sel_hi:[1,1,1]
	v_pk_fma_f32 v[236:237], v[194:195], v[244:245], v[236:237] op_sel:[1,0,0] op_sel_hi:[1,1,1]
	v_pk_fma_f32 v[238:239], v[194:195], v[246:247], v[238:239] op_sel:[1,0,0] op_sel_hi:[1,1,1]
	s_nop 1
	v_permlane32_swap_b32_e32 v216, v232
	v_permlane32_swap_b32_e32 v217, v233
	v_permlane32_swap_b32_e32 v228, v236
	v_permlane32_swap_b32_e32 v229, v237
	v_permlane32_swap_b32_e32 v226, v234
	v_permlane32_swap_b32_e32 v227, v235
	v_permlane32_swap_b32_e32 v230, v238
	v_permlane32_swap_b32_e32 v231, v239
	v_pk_add_f32 v[216:217], v[216:217], v[232:233]
	v_pk_add_f32 v[228:229], v[228:229], v[236:237]
	v_pk_add_f32 v[226:227], v[226:227], v[234:235]
	v_pk_add_f32 v[230:231], v[230:231], v[238:239]
	s_nop 1
	v_permlane16_swap_b32_e32 v216, v228
	v_permlane16_swap_b32_e32 v217, v229
	v_permlane16_swap_b32_e32 v226, v230
	v_permlane16_swap_b32_e32 v227, v231
	v_pk_add_f32 v[216:217], v[216:217], v[228:229]
	v_pk_add_f32 v[226:227], v[226:227], v[230:231]
	s_nop 1
	v_add_f32_dpp v216, v216, v216 row_shl:8 row_mask:0xf bank_mask:0x3
	v_add_f32_dpp v217, v217, v217 row_shl:8 row_mask:0xf bank_mask:0x3
	v_add_f32_dpp v216, v226, v226 row_shr:8 row_mask:0xf bank_mask:0xc
	v_add_f32_dpp v217, v227, v227 row_shr:8 row_mask:0xf bank_mask:0xc
	global_store_dwordx2 v[188:189], v[216:217], off
	s_cmp_gt_u32 s36, 13
	s_cselect_b64 s[28:29], -1, 0
	s_and_b64 vcc, exec, s[28:29]
	s_cbranch_vccnz .LBB0_1649
; DI void up_issue(u32x4 (&W)[16], u32 (&pj)[16], const u32* pl, const unsigned char* wbase, int grp) {
; #pragma unroll
;   for (int j = 0; j < 16; ++j) {
;     pj[j] = pl[8 * j + grp];
;     W[j] = *(const u32x4*)(wbase + (size_t)(pj[j] >> 16) * 1024);
;   }
; DI void peer_up_phase(const Params& p, unsigned char* smem, int layer, u32* ctr) {
;     ...
;       for (int tl = 0; tl < 16; tl += 2) {
;         up_issue(WB, pB, pl + (tl + 1) * 128, wbase, grp);
;         __builtin_amdgcn_sched_barrier(0);
;         up_math(WA, pA, ybase + (size_t)tl * 1024, lane);
;         __builtin_amdgcn_sched_barrier(0);
;         if (tl + 2 < 16) up_issue(WA, pA, pl + (tl + 2) * 128, wbase, grp);
;         __builtin_amdgcn_sched_barrier(0);
;         up_math(WB, pB, ybase + (size_t)(tl + 1) * 1024, lane);
	ds_read_u16_d16_hi v178, v145 offset:512
	ds_read_u16_d16_hi v179, v145 offset:544
	ds_read_u16_d16_hi v180, v145 offset:576
	ds_read_u16_d16_hi v181, v145 offset:608
	ds_read_u16_d16_hi v182, v145 offset:640
	ds_read_u16_d16_hi v183, v145 offset:672
	ds_read_u16_d16_hi v184, v145 offset:704
	ds_read_u16_d16_hi v185, v145 offset:736
	ds_read_u16_d16_hi v186, v145 offset:768
	ds_read_u16_d16_hi v187, v145 offset:800
	ds_read_u16_d16_hi v190, v145 offset:832
	ds_read_u16_d16_hi v191, v145 offset:864
	ds_read_u16_d16_hi v192, v145 offset:896
	ds_read_u16_d16_hi v193, v145 offset:928
	ds_read_u16_d16_hi v194, v145 offset:960
	ds_read_u16_d16_hi v195, v145 offset:992
	ds_read_u16 v4, v145 offset:514
	ds_read_u16 v8, v145 offset:546
	ds_read_u16 v12, v145 offset:578
	ds_read_u16 v16, v145 offset:610
	ds_read_u16 v20, v145 offset:642
	ds_read_u16 v24, v145 offset:674
	ds_read_u16 v28, v145 offset:706
	ds_read_u16 v32, v145 offset:738
	ds_read_u16 v36, v145 offset:770
	ds_read_u16 v40, v145 offset:802
	ds_read_u16 v44, v145 offset:834
	ds_read_u16 v48, v145 offset:866
	ds_read_u16 v52, v145 offset:898
	ds_read_u16 v56, v145 offset:930
	ds_read_u16 v60, v145 offset:962
	ds_read_u16 v64, v145 offset:994
	s_waitcnt lgkmcnt(15)
	v_lshl_add_u32 v4, v4, 10, v250
	global_load_dwordx4 v[4:7], v4, s[98:99]
	s_waitcnt lgkmcnt(14)
	v_lshl_add_u32 v8, v8, 10, v250
	global_load_dwordx4 v[8:11], v8, s[98:99]
	s_waitcnt lgkmcnt(13)
	v_lshl_add_u32 v12, v12, 10, v250
	global_load_dwordx4 v[12:15], v12, s[98:99]
	s_waitcnt lgkmcnt(12)
	v_lshl_add_u32 v16, v16, 10, v250
	global_load_dwordx4 v[16:19], v16, s[98:99]
	s_waitcnt lgkmcnt(11)
	v_lshl_add_u32 v20, v20, 10, v250
	global_load_dwordx4 v[20:23], v20, s[98:99]
	s_waitcnt lgkmcnt(10)
	v_lshl_add_u32 v24, v24, 10, v250
	global_load_dwordx4 v[24:27], v24, s[98:99]
	s_waitcnt lgkmcnt(9)
	v_lshl_add_u32 v28, v28, 10, v250
	global_load_dwordx4 v[28:31], v28, s[98:99]
	s_waitcnt lgkmcnt(8)
	v_lshl_add_u32 v32, v32, 10, v250
	global_load_dwordx4 v[32:35], v32, s[98:99]
	s_waitcnt lgkmcnt(7)
	v_lshl_add_u32 v36, v36, 10, v250
	global_load_dwordx4 v[36:39], v36, s[98:99]
	s_waitcnt lgkmcnt(6)
	v_lshl_add_u32 v40, v40, 10, v250
	global_load_dwordx4 v[40:43], v40, s[98:99]
	s_waitcnt lgkmcnt(5)
	v_lshl_add_u32 v44, v44, 10, v250
	global_load_dwordx4 v[44:47], v44, s[98:99]
	s_waitcnt lgkmcnt(4)
	v_lshl_add_u32 v48, v48, 10, v250
	global_load_dwordx4 v[48:51], v48, s[98:99]
	s_waitcnt lgkmcnt(3)
	v_lshl_add_u32 v52, v52, 10, v250
	global_load_dwordx4 v[52:55], v52, s[98:99]
	s_waitcnt lgkmcnt(2)
	v_lshl_add_u32 v56, v56, 10, v250
	global_load_dwordx4 v[56:59], v56, s[98:99]
	s_waitcnt lgkmcnt(1)
	v_lshl_add_u32 v60, v60, 10, v250
	global_load_dwordx4 v[60:63], v60, s[98:99]
	s_waitcnt lgkmcnt(0)
	v_lshl_add_u32 v64, v64, 10, v250
	global_load_dwordx4 v[64:67], v64, s[98:99]
	s_branch .LBB0_1649
